# v8_epibranch
# speedup vs baseline: 1.0404x; 1.0037x over previous
; __device__ __forceinline__ u32x4 pack8(const f32x4 v0, const f32x4 v1) { u32x4 w; w.x = cvt_pk_bf16(v0[0], v0[1]); w.y = cvt_pk_bf16(v0[2], v0[3]); w.z = cvt_pk_bf16(v1[0], v1[1]); w.w = cvt_pk_bf16(v1[2], v1[3]); return w; }
; __device__ __forceinline__ void unpack8(const u32x4 w, f32x4& lo, f32x4& hi) { lo = (f32x4){bf_lo(w.x), bf_hi(w.x), bf_lo(w.y), bf_hi(w.y)}; hi = (f32x4){bf_lo(w.z), bf_hi(w.z), bf_lo(w.w), bf_hi(w.w)}; }
;     __device__ __forceinline__ void operator()(AccT& acc, const Unit& u, int wr, int wc, int fr, int fq) const {
;     ...
;             for (int m = 0; m < 4; ++m) { const size_t row = (size_t)(row0 + ai * 128 + m * 16);
; #pragma unroll
;                 for (int bj = 0; bj < 2; ++bj) { f32x4 p0, p1; unpack8(*(const u32x4*)(PROJ + row * DIN + 8192 + col0 + bj * 128), p0, p1);
; #pragma unroll
;                     for (int j = 0; j < 4; ++j) { p0[j] = fmaxf(p0[j], TINY); p1[j] = fmaxf(p1[j], TINY); }
;                     if (u.kind == 0) { f32x4 s0, s1; unpack8(*(const u32x4*)(PROJ + row * DIN + 4096 + col0 + bj * 128), s0, s1);
; #pragma unroll
;                         for (int j = 0; j < 4; ++j) { acc[ai][bj][m][0][j] *= s0[j] * __builtin_amdgcn_rcpf(p0[j]); acc[ai][bj][m][1][j] *= s1[j] * __builtin_amdgcn_rcpf(p1[j]); } }
;                     else *(u32x4*)(MG + row * DM + col0 + bj * 128) = pack8(acc[ai][bj][m][0] * p0, acc[ai][bj][m][1] * p1); } }
.LBB0_488:
	v_mov_b32_e32 v133, v254
	s_lshl_b32 s4, s66, 8
	v_lshrrev_b32_e32 v132, 1, v133
	v_and_or_b32 v132, v132, 24, s4
	v_and_or_b32 v133, v133, 15, s83
	v_or_b32_e32 v132, s84, v132
	v_lshl_add_u32 v134, s3, 8, v133
	v_mov_b64_e32 v[136:137], s[20:21]
	v_ashrrev_i32_e32 v133, 31, v132
	v_mad_i64_i32 v[136:137], s[4:5], v134, s78, v[136:137]
	v_lshl_add_u64 v[136:137], v[132:133], 1, v[136:137]
	v_add_co_u32_e32 v138, vcc, s77, v136
	v_ashrrev_i32_e32 v135, 31, v134
	s_nop 0
	v_addc_co_u32_e32 v139, vcc, 0, v137, vcc
	s_cmp_lg_u32 s8, 0
	v_lshlrev_b64 v[138:139], 13, v[134:135]
	s_cselect_b64 s[16:17], -1, 0
	v_lshl_add_u64 v[138:139], s[26:27], 0, v[138:139]
	s_and_b64 vcc, exec, s[16:17]
	v_lshl_add_u64 v[138:139], v[132:133], 1, v[138:139]
	s_mov_b64 s[4:5], 0x4000
	v_lshl_add_u64 v[226:227], v[136:137], 0, s[4:5]
	global_load_dwordx4 v[162:165], v[226:227], off
	global_load_dwordx4 v[166:169], v[226:227], off offset:256
	s_mov_b64 s[4:5], 0x64000
	v_lshl_add_u64 v[226:227], v[136:137], 0, s[4:5]
	global_load_dwordx4 v[170:173], v[226:227], off
	global_load_dwordx4 v[174:177], v[226:227], off offset:256
	s_mov_b64 s[4:5], 0xc4000
	v_lshl_add_u64 v[226:227], v[136:137], 0, s[4:5]
	global_load_dwordx4 v[178:181], v[226:227], off
	global_load_dwordx4 v[182:185], v[226:227], off offset:256
	s_mov_b64 s[4:5], 0x124000
	v_lshl_add_u64 v[226:227], v[136:137], 0, s[4:5]
	global_load_dwordx4 v[186:189], v[226:227], off
	global_load_dwordx4 v[190:193], v[226:227], off offset:256
	s_mov_b64 s[4:5], 0x304000
	v_lshl_add_u64 v[226:227], v[136:137], 0, s[4:5]
	global_load_dwordx4 v[194:197], v[226:227], off
	global_load_dwordx4 v[198:201], v[226:227], off offset:256
	s_mov_b64 s[4:5], 0x364000
	v_lshl_add_u64 v[226:227], v[136:137], 0, s[4:5]
	global_load_dwordx4 v[202:205], v[226:227], off
	global_load_dwordx4 v[206:209], v[226:227], off offset:256
	s_mov_b64 s[4:5], 0x3c4000
	v_lshl_add_u64 v[226:227], v[136:137], 0, s[4:5]
	global_load_dwordx4 v[210:213], v[226:227], off
	global_load_dwordx4 v[214:217], v[226:227], off offset:256
	s_mov_b64 s[4:5], 0x424000
	v_lshl_add_u64 v[226:227], v[136:137], 0, s[4:5]
	global_load_dwordx4 v[218:221], v[226:227], off
	global_load_dwordx4 v[222:225], v[226:227], off offset:256
	s_cmp_lg_u32 s8, 0
	s_cbranch_scc1 .Lbr_kind1
	s_mov_b64 s[4:5], 0x2000
	v_lshl_add_u64 v[226:227], v[136:137], 0, s[4:5]
	global_load_dwordx4 v[228:231], v[226:227], off
	global_load_dwordx4 v[232:235], v[226:227], off offset:256
	s_mov_b64 s[4:5], 0x62000
	v_lshl_add_u64 v[226:227], v[136:137], 0, s[4:5]
	global_load_dwordx4 v[236:239], v[226:227], off
	global_load_dwordx4 v[240:243], v[226:227], off offset:256
	s_mov_b64 s[4:5], 0xc2000
	v_lshl_add_u64 v[226:227], v[136:137], 0, s[4:5]
	global_load_dwordx4 v[244:247], v[226:227], off
	global_load_dwordx4 v[248:251], v[226:227], off offset:256
	s_waitcnt vmcnt(5)
	v_lshlrev_b32_e32 v140, 16, v162
	v_and_b32_e32 v141, 0xffff0000, v162
	v_lshlrev_b32_e32 v142, 16, v163
	v_and_b32_e32 v143, 0xffff0000, v163
	v_lshlrev_b32_e32 v144, 16, v164
	v_and_b32_e32 v145, 0xffff0000, v164
	v_lshlrev_b32_e32 v146, 16, v165
	v_and_b32_e32 v147, 0xffff0000, v165
	v_max_f32_e32 v140, v140, v140
	v_max_f32_e32 v141, v141, v141
	v_max_f32_e32 v142, v142, v142
	v_max_f32_e32 v143, v143, v143
	v_max_f32_e32 v144, v144, v144
	v_max_f32_e32 v145, v145, v145
	v_max_f32_e32 v146, v146, v146
	v_max_f32_e32 v147, v147, v147
	v_max_f32_e32 v140, 0xda24260, v140
	v_max_f32_e32 v141, 0xda24260, v141
	v_max_f32_e32 v142, 0xda24260, v142
	v_max_f32_e32 v143, 0xda24260, v143
	v_max_f32_e32 v144, 0xda24260, v144
	v_max_f32_e32 v145, 0xda24260, v145
	v_max_f32_e32 v146, 0xda24260, v146
	v_max_f32_e32 v147, 0xda24260, v147
	v_rcp_f32_e32 v140, v140
	v_rcp_f32_e32 v141, v141
	v_rcp_f32_e32 v142, v142
	v_rcp_f32_e32 v143, v143
	v_rcp_f32_e32 v144, v144
	v_rcp_f32_e32 v145, v145
	v_rcp_f32_e32 v146, v146
	v_rcp_f32_e32 v147, v147
	v_lshlrev_b32_e32 v154, 16, v228
	v_and_b32_e32 v155, 0xffff0000, v228
	v_lshlrev_b32_e32 v156, 16, v229
	v_and_b32_e32 v157, 0xffff0000, v229
	v_lshlrev_b32_e32 v158, 16, v230
	v_and_b32_e32 v159, 0xffff0000, v230
	v_lshlrev_b32_e32 v160, 16, v231
	v_and_b32_e32 v161, 0xffff0000, v231
	s_mov_b64 s[4:5], 0x122000
	v_lshl_add_u64 v[226:227], v[136:137], 0, s[4:5]
	global_load_dwordx4 v[162:165], v[226:227], off
	v_pk_mul_f32 v[140:141], v[140:141], v[154:155]
	v_pk_mul_f32 v[142:143], v[142:143], v[156:157]
	v_pk_mul_f32 v[144:145], v[144:145], v[158:159]
	v_pk_mul_f32 v[146:147], v[146:147], v[160:161]
	v_pk_mul_f32 v[124:125], v[124:125], v[140:141]
	v_pk_mul_f32 v[126:127], v[126:127], v[142:143]
	v_pk_mul_f32 v[120:121], v[120:121], v[144:145]
	v_pk_mul_f32 v[122:123], v[122:123], v[146:147]
	s_waitcnt vmcnt(5)
; __device__ __forceinline__ u32x4 pack8(const f32x4 v0, const f32x4 v1) { u32x4 w; w.x = cvt_pk_bf16(v0[0], v0[1]); w.y = cvt_pk_bf16(v0[2], v0[3]); w.z = cvt_pk_bf16(v1[0], v1[1]); w.w = cvt_pk_bf16(v1[2], v1[3]); return w; }
; __device__ __forceinline__ void unpack8(const u32x4 w, f32x4& lo, f32x4& hi) { lo = (f32x4){bf_lo(w.x), bf_hi(w.x), bf_lo(w.y), bf_hi(w.y)}; hi = (f32x4){bf_lo(w.z), bf_hi(w.z), bf_lo(w.w), bf_hi(w.w)}; }
;     __device__ __forceinline__ void operator()(AccT& acc, const Unit& u, int wr, int wc, int fr, int fq) const {
;     ...
;             for (int m = 0; m < 4; ++m) { const size_t row = (size_t)(row0 + ai * 128 + m * 16);
; #pragma unroll
;                 for (int bj = 0; bj < 2; ++bj) { f32x4 p0, p1; unpack8(*(const u32x4*)(PROJ + row * DIN + 8192 + col0 + bj * 128), p0, p1);
; #pragma unroll
;                     for (int j = 0; j < 4; ++j) { p0[j] = fmaxf(p0[j], TINY); p1[j] = fmaxf(p1[j], TINY); }
;                     if (u.kind == 0) { f32x4 s0, s1; unpack8(*(const u32x4*)(PROJ + row * DIN + 4096 + col0 + bj * 128), s0, s1);
; #pragma unroll
;                         for (int j = 0; j < 4; ++j) { acc[ai][bj][m][0][j] *= s0[j] * __builtin_amdgcn_rcpf(p0[j]); acc[ai][bj][m][1][j] *= s1[j] * __builtin_amdgcn_rcpf(p1[j]); } }
;                     else *(u32x4*)(MG + row * DM + col0 + bj * 128) = pack8(acc[ai][bj][m][0] * p0, acc[ai][bj][m][1] * p1); } }
	v_lshlrev_b32_e32 v140, 16, v166
	v_and_b32_e32 v141, 0xffff0000, v166
	v_lshlrev_b32_e32 v142, 16, v167
	v_and_b32_e32 v143, 0xffff0000, v167
	v_lshlrev_b32_e32 v144, 16, v168
	v_and_b32_e32 v145, 0xffff0000, v168
	v_lshlrev_b32_e32 v146, 16, v169
	v_and_b32_e32 v147, 0xffff0000, v169
	v_max_f32_e32 v140, v140, v140
	v_max_f32_e32 v141, v141, v141
	v_max_f32_e32 v142, v142, v142
	v_max_f32_e32 v143, v143, v143
	v_max_f32_e32 v144, v144, v144
	v_max_f32_e32 v145, v145, v145
	v_max_f32_e32 v146, v146, v146
	v_max_f32_e32 v147, v147, v147
	v_max_f32_e32 v140, 0xda24260, v140
	v_max_f32_e32 v141, 0xda24260, v141
	v_max_f32_e32 v142, 0xda24260, v142
	v_max_f32_e32 v143, 0xda24260, v143
	v_max_f32_e32 v144, 0xda24260, v144
	v_max_f32_e32 v145, 0xda24260, v145
	v_max_f32_e32 v146, 0xda24260, v146
	v_max_f32_e32 v147, 0xda24260, v147
	v_rcp_f32_e32 v140, v140
	v_rcp_f32_e32 v141, v141
	v_rcp_f32_e32 v142, v142
	v_rcp_f32_e32 v143, v143
	v_rcp_f32_e32 v144, v144
	v_rcp_f32_e32 v145, v145
	v_rcp_f32_e32 v146, v146
	v_rcp_f32_e32 v147, v147
	v_lshlrev_b32_e32 v154, 16, v232
	v_and_b32_e32 v155, 0xffff0000, v232
	v_lshlrev_b32_e32 v156, 16, v233
	v_and_b32_e32 v157, 0xffff0000, v233
	v_lshlrev_b32_e32 v158, 16, v234
	v_and_b32_e32 v159, 0xffff0000, v234
	v_lshlrev_b32_e32 v160, 16, v235
	v_and_b32_e32 v161, 0xffff0000, v235
	global_load_dwordx4 v[166:169], v[226:227], off offset:256
	v_pk_mul_f32 v[140:141], v[140:141], v[154:155]
	v_pk_mul_f32 v[142:143], v[142:143], v[156:157]
	v_pk_mul_f32 v[144:145], v[144:145], v[158:159]
	v_pk_mul_f32 v[146:147], v[146:147], v[160:161]
	v_pk_mul_f32 v[92:93], v[92:93], v[140:141]
	v_pk_mul_f32 v[94:95], v[94:95], v[142:143]
	v_pk_mul_f32 v[88:89], v[88:89], v[144:145]
	v_pk_mul_f32 v[90:91], v[90:91], v[146:147]
	s_waitcnt vmcnt(5)
	v_lshlrev_b32_e32 v140, 16, v170
	v_and_b32_e32 v141, 0xffff0000, v170
	v_lshlrev_b32_e32 v142, 16, v171
	v_and_b32_e32 v143, 0xffff0000, v171
	v_lshlrev_b32_e32 v144, 16, v172
	v_and_b32_e32 v145, 0xffff0000, v172
	v_lshlrev_b32_e32 v146, 16, v173
	v_and_b32_e32 v147, 0xffff0000, v173
	v_max_f32_e32 v140, v140, v140
	v_max_f32_e32 v141, v141, v141
	v_max_f32_e32 v142, v142, v142
	v_max_f32_e32 v143, v143, v143
	v_max_f32_e32 v144, v144, v144
	v_max_f32_e32 v145, v145, v145
	v_max_f32_e32 v146, v146, v146
	v_max_f32_e32 v147, v147, v147
	v_max_f32_e32 v140, 0xda24260, v140
	v_max_f32_e32 v141, 0xda24260, v141
	v_max_f32_e32 v142, 0xda24260, v142
	v_max_f32_e32 v143, 0xda24260, v143
	v_max_f32_e32 v144, 0xda24260, v144
	v_max_f32_e32 v145, 0xda24260, v145
	v_max_f32_e32 v146, 0xda24260, v146
	v_max_f32_e32 v147, 0xda24260, v147
	v_rcp_f32_e32 v140, v140
	v_rcp_f32_e32 v141, v141
	v_rcp_f32_e32 v142, v142
	v_rcp_f32_e32 v143, v143
	v_rcp_f32_e32 v144, v144
	v_rcp_f32_e32 v145, v145
	v_rcp_f32_e32 v146, v146
	v_rcp_f32_e32 v147, v147
	v_lshlrev_b32_e32 v154, 16, v236
	v_and_b32_e32 v155, 0xffff0000, v236
	v_lshlrev_b32_e32 v156, 16, v237
	v_and_b32_e32 v157, 0xffff0000, v237
	v_lshlrev_b32_e32 v158, 16, v238
	v_and_b32_e32 v159, 0xffff0000, v238
	v_lshlrev_b32_e32 v160, 16, v239
	v_and_b32_e32 v161, 0xffff0000, v239
	s_mov_b64 s[4:5], 0x302000
	v_lshl_add_u64 v[226:227], v[136:137], 0, s[4:5]
	global_load_dwordx4 v[170:173], v[226:227], off
	v_pk_mul_f32 v[140:141], v[140:141], v[154:155]
	v_pk_mul_f32 v[142:143], v[142:143], v[156:157]
	v_pk_mul_f32 v[144:145], v[144:145], v[158:159]
	v_pk_mul_f32 v[146:147], v[146:147], v[160:161]
	v_pk_mul_f32 v[116:117], v[116:117], v[140:141]
	v_pk_mul_f32 v[118:119], v[118:119], v[142:143]
	v_pk_mul_f32 v[112:113], v[112:113], v[144:145]
	v_pk_mul_f32 v[114:115], v[114:115], v[146:147]
	s_waitcnt vmcnt(5)
	v_lshlrev_b32_e32 v140, 16, v174
	v_and_b32_e32 v141, 0xffff0000, v174
	v_lshlrev_b32_e32 v142, 16, v175
	v_and_b32_e32 v143, 0xffff0000, v175
	v_lshlrev_b32_e32 v144, 16, v176
	v_and_b32_e32 v145, 0xffff0000, v176
	v_lshlrev_b32_e32 v146, 16, v177
	v_and_b32_e32 v147, 0xffff0000, v177
	v_max_f32_e32 v140, v140, v140
	v_max_f32_e32 v141, v141, v141
	v_max_f32_e32 v142, v142, v142
	v_max_f32_e32 v143, v143, v143
	v_max_f32_e32 v144, v144, v144
	v_max_f32_e32 v145, v145, v145
	v_max_f32_e32 v146, v146, v146
	v_max_f32_e32 v147, v147, v147
	v_max_f32_e32 v140, 0xda24260, v140
	v_max_f32_e32 v141, 0xda24260, v141
	v_max_f32_e32 v142, 0xda24260, v142
	v_max_f32_e32 v143, 0xda24260, v143
	v_max_f32_e32 v144, 0xda24260, v144
	v_max_f32_e32 v145, 0xda24260, v145
	v_max_f32_e32 v146, 0xda24260, v146
	v_max_f32_e32 v147, 0xda24260, v147
	v_rcp_f32_e32 v140, v140
	v_rcp_f32_e32 v141, v141
	v_rcp_f32_e32 v142, v142
	v_rcp_f32_e32 v143, v143
	v_rcp_f32_e32 v144, v144
	v_rcp_f32_e32 v145, v145
	v_rcp_f32_e32 v146, v146
	v_rcp_f32_e32 v147, v147
	v_lshlrev_b32_e32 v154, 16, v240
	v_and_b32_e32 v155, 0xffff0000, v240
	v_lshlrev_b32_e32 v156, 16, v241
	v_and_b32_e32 v157, 0xffff0000, v241
	v_lshlrev_b32_e32 v158, 16, v242
	v_and_b32_e32 v159, 0xffff0000, v242
	v_lshlrev_b32_e32 v160, 16, v243
	v_and_b32_e32 v161, 0xffff0000, v243
	global_load_dwordx4 v[174:177], v[226:227], off offset:256
	v_pk_mul_f32 v[140:141], v[140:141], v[154:155]
	v_pk_mul_f32 v[142:143], v[142:143], v[156:157]
	v_pk_mul_f32 v[144:145], v[144:145], v[158:159]
	v_pk_mul_f32 v[146:147], v[146:147], v[160:161]
	v_pk_mul_f32 v[84:85], v[84:85], v[140:141]
	v_pk_mul_f32 v[86:87], v[86:87], v[142:143]
	v_pk_mul_f32 v[80:81], v[80:81], v[144:145]
	v_pk_mul_f32 v[82:83], v[82:83], v[146:147]
	s_waitcnt vmcnt(5)
; __device__ __forceinline__ u32x4 pack8(const f32x4 v0, const f32x4 v1) { u32x4 w; w.x = cvt_pk_bf16(v0[0], v0[1]); w.y = cvt_pk_bf16(v0[2], v0[3]); w.z = cvt_pk_bf16(v1[0], v1[1]); w.w = cvt_pk_bf16(v1[2], v1[3]); return w; }
; __device__ __forceinline__ void unpack8(const u32x4 w, f32x4& lo, f32x4& hi) { lo = (f32x4){bf_lo(w.x), bf_hi(w.x), bf_lo(w.y), bf_hi(w.y)}; hi = (f32x4){bf_lo(w.z), bf_hi(w.z), bf_lo(w.w), bf_hi(w.w)}; }
;     __device__ __forceinline__ void operator()(AccT& acc, const Unit& u, int wr, int wc, int fr, int fq) const {
;     ...
;             for (int m = 0; m < 4; ++m) { const size_t row = (size_t)(row0 + ai * 128 + m * 16);
; #pragma unroll
;                 for (int bj = 0; bj < 2; ++bj) { f32x4 p0, p1; unpack8(*(const u32x4*)(PROJ + row * DIN + 8192 + col0 + bj * 128), p0, p1);
; #pragma unroll
;                     for (int j = 0; j < 4; ++j) { p0[j] = fmaxf(p0[j], TINY); p1[j] = fmaxf(p1[j], TINY); }
;                     if (u.kind == 0) { f32x4 s0, s1; unpack8(*(const u32x4*)(PROJ + row * DIN + 4096 + col0 + bj * 128), s0, s1);
; #pragma unroll
;                         for (int j = 0; j < 4; ++j) { acc[ai][bj][m][0][j] *= s0[j] * __builtin_amdgcn_rcpf(p0[j]); acc[ai][bj][m][1][j] *= s1[j] * __builtin_amdgcn_rcpf(p1[j]); } }
;                     else *(u32x4*)(MG + row * DM + col0 + bj * 128) = pack8(acc[ai][bj][m][0] * p0, acc[ai][bj][m][1] * p1); } }
	v_lshlrev_b32_e32 v140, 16, v178
	v_and_b32_e32 v141, 0xffff0000, v178
	v_lshlrev_b32_e32 v142, 16, v179
	v_and_b32_e32 v143, 0xffff0000, v179
	v_lshlrev_b32_e32 v144, 16, v180
	v_and_b32_e32 v145, 0xffff0000, v180
	v_lshlrev_b32_e32 v146, 16, v181
	v_and_b32_e32 v147, 0xffff0000, v181
	v_max_f32_e32 v140, v140, v140
	v_max_f32_e32 v141, v141, v141
	v_max_f32_e32 v142, v142, v142
	v_max_f32_e32 v143, v143, v143
	v_max_f32_e32 v144, v144, v144
	v_max_f32_e32 v145, v145, v145
	v_max_f32_e32 v146, v146, v146
	v_max_f32_e32 v147, v147, v147
	v_max_f32_e32 v140, 0xda24260, v140
	v_max_f32_e32 v141, 0xda24260, v141
	v_max_f32_e32 v142, 0xda24260, v142
	v_max_f32_e32 v143, 0xda24260, v143
	v_max_f32_e32 v144, 0xda24260, v144
	v_max_f32_e32 v145, 0xda24260, v145
	v_max_f32_e32 v146, 0xda24260, v146
	v_max_f32_e32 v147, 0xda24260, v147
	v_rcp_f32_e32 v140, v140
	v_rcp_f32_e32 v141, v141
	v_rcp_f32_e32 v142, v142
	v_rcp_f32_e32 v143, v143
	v_rcp_f32_e32 v144, v144
	v_rcp_f32_e32 v145, v145
	v_rcp_f32_e32 v146, v146
	v_rcp_f32_e32 v147, v147
	v_lshlrev_b32_e32 v154, 16, v244
	v_and_b32_e32 v155, 0xffff0000, v244
	v_lshlrev_b32_e32 v156, 16, v245
	v_and_b32_e32 v157, 0xffff0000, v245
	v_lshlrev_b32_e32 v158, 16, v246
	v_and_b32_e32 v159, 0xffff0000, v246
	v_lshlrev_b32_e32 v160, 16, v247
	v_and_b32_e32 v161, 0xffff0000, v247
	s_mov_b64 s[4:5], 0x362000
	v_lshl_add_u64 v[226:227], v[136:137], 0, s[4:5]
	global_load_dwordx4 v[178:181], v[226:227], off
	v_pk_mul_f32 v[140:141], v[140:141], v[154:155]
	v_pk_mul_f32 v[142:143], v[142:143], v[156:157]
	v_pk_mul_f32 v[144:145], v[144:145], v[158:159]
	v_pk_mul_f32 v[146:147], v[146:147], v[160:161]
	v_pk_mul_f32 v[108:109], v[108:109], v[140:141]
	v_pk_mul_f32 v[110:111], v[110:111], v[142:143]
	v_pk_mul_f32 v[104:105], v[104:105], v[144:145]
	v_pk_mul_f32 v[106:107], v[106:107], v[146:147]
	s_waitcnt vmcnt(5)
	v_lshlrev_b32_e32 v140, 16, v182
	v_and_b32_e32 v141, 0xffff0000, v182
	v_lshlrev_b32_e32 v142, 16, v183
	v_and_b32_e32 v143, 0xffff0000, v183
	v_lshlrev_b32_e32 v144, 16, v184
	v_and_b32_e32 v145, 0xffff0000, v184
	v_lshlrev_b32_e32 v146, 16, v185
	v_and_b32_e32 v147, 0xffff0000, v185
	v_max_f32_e32 v140, v140, v140
	v_max_f32_e32 v141, v141, v141
	v_max_f32_e32 v142, v142, v142
	v_max_f32_e32 v143, v143, v143
	v_max_f32_e32 v144, v144, v144
	v_max_f32_e32 v145, v145, v145
	v_max_f32_e32 v146, v146, v146
	v_max_f32_e32 v147, v147, v147
	v_max_f32_e32 v140, 0xda24260, v140
	v_max_f32_e32 v141, 0xda24260, v141
	v_max_f32_e32 v142, 0xda24260, v142
	v_max_f32_e32 v143, 0xda24260, v143
	v_max_f32_e32 v144, 0xda24260, v144
	v_max_f32_e32 v145, 0xda24260, v145
	v_max_f32_e32 v146, 0xda24260, v146
	v_max_f32_e32 v147, 0xda24260, v147
	v_rcp_f32_e32 v140, v140
	v_rcp_f32_e32 v141, v141
	v_rcp_f32_e32 v142, v142
	v_rcp_f32_e32 v143, v143
	v_rcp_f32_e32 v144, v144
	v_rcp_f32_e32 v145, v145
	v_rcp_f32_e32 v146, v146
	v_rcp_f32_e32 v147, v147
	v_lshlrev_b32_e32 v154, 16, v248
	v_and_b32_e32 v155, 0xffff0000, v248
	v_lshlrev_b32_e32 v156, 16, v249
	v_and_b32_e32 v157, 0xffff0000, v249
	v_lshlrev_b32_e32 v158, 16, v250
	v_and_b32_e32 v159, 0xffff0000, v250
	v_lshlrev_b32_e32 v160, 16, v251
	v_and_b32_e32 v161, 0xffff0000, v251
	global_load_dwordx4 v[182:185], v[226:227], off offset:256
	v_pk_mul_f32 v[140:141], v[140:141], v[154:155]
	v_pk_mul_f32 v[142:143], v[142:143], v[156:157]
	v_pk_mul_f32 v[144:145], v[144:145], v[158:159]
	v_pk_mul_f32 v[146:147], v[146:147], v[160:161]
	v_pk_mul_f32 v[76:77], v[76:77], v[140:141]
	v_pk_mul_f32 v[78:79], v[78:79], v[142:143]
	v_pk_mul_f32 v[72:73], v[72:73], v[144:145]
	v_pk_mul_f32 v[74:75], v[74:75], v[146:147]
	s_waitcnt vmcnt(5)
	v_lshlrev_b32_e32 v140, 16, v186
	v_and_b32_e32 v141, 0xffff0000, v186
	v_lshlrev_b32_e32 v142, 16, v187
	v_and_b32_e32 v143, 0xffff0000, v187
	v_lshlrev_b32_e32 v144, 16, v188
	v_and_b32_e32 v145, 0xffff0000, v188
	v_lshlrev_b32_e32 v146, 16, v189
	v_and_b32_e32 v147, 0xffff0000, v189
	v_max_f32_e32 v140, v140, v140
	v_max_f32_e32 v141, v141, v141
	v_max_f32_e32 v142, v142, v142
	v_max_f32_e32 v143, v143, v143
	v_max_f32_e32 v144, v144, v144
	v_max_f32_e32 v145, v145, v145
	v_max_f32_e32 v146, v146, v146
	v_max_f32_e32 v147, v147, v147
	v_max_f32_e32 v140, 0xda24260, v140
	v_max_f32_e32 v141, 0xda24260, v141
	v_max_f32_e32 v142, 0xda24260, v142
	v_max_f32_e32 v143, 0xda24260, v143
	v_max_f32_e32 v144, 0xda24260, v144
	v_max_f32_e32 v145, 0xda24260, v145
	v_max_f32_e32 v146, 0xda24260, v146
	v_max_f32_e32 v147, 0xda24260, v147
	v_rcp_f32_e32 v140, v140
	v_rcp_f32_e32 v141, v141
	v_rcp_f32_e32 v142, v142
	v_rcp_f32_e32 v143, v143
	v_rcp_f32_e32 v144, v144
	v_rcp_f32_e32 v145, v145
	v_rcp_f32_e32 v146, v146
	v_rcp_f32_e32 v147, v147
	v_lshlrev_b32_e32 v154, 16, v162
	v_and_b32_e32 v155, 0xffff0000, v162
	v_lshlrev_b32_e32 v156, 16, v163
	v_and_b32_e32 v157, 0xffff0000, v163
	v_lshlrev_b32_e32 v158, 16, v164
	v_and_b32_e32 v159, 0xffff0000, v164
	v_lshlrev_b32_e32 v160, 16, v165
	v_and_b32_e32 v161, 0xffff0000, v165
	s_mov_b64 s[4:5], 0x3c2000
	v_lshl_add_u64 v[226:227], v[136:137], 0, s[4:5]
	global_load_dwordx4 v[186:189], v[226:227], off
	v_pk_mul_f32 v[140:141], v[140:141], v[154:155]
	v_pk_mul_f32 v[142:143], v[142:143], v[156:157]
	v_pk_mul_f32 v[144:145], v[144:145], v[158:159]
	v_pk_mul_f32 v[146:147], v[146:147], v[160:161]
	v_pk_mul_f32 v[100:101], v[100:101], v[140:141]
	v_pk_mul_f32 v[102:103], v[102:103], v[142:143]
	v_pk_mul_f32 v[96:97], v[96:97], v[144:145]
	v_pk_mul_f32 v[98:99], v[98:99], v[146:147]
	s_waitcnt vmcnt(5)
; __device__ __forceinline__ u32x4 pack8(const f32x4 v0, const f32x4 v1) { u32x4 w; w.x = cvt_pk_bf16(v0[0], v0[1]); w.y = cvt_pk_bf16(v0[2], v0[3]); w.z = cvt_pk_bf16(v1[0], v1[1]); w.w = cvt_pk_bf16(v1[2], v1[3]); return w; }
; __device__ __forceinline__ void unpack8(const u32x4 w, f32x4& lo, f32x4& hi) { lo = (f32x4){bf_lo(w.x), bf_hi(w.x), bf_lo(w.y), bf_hi(w.y)}; hi = (f32x4){bf_lo(w.z), bf_hi(w.z), bf_lo(w.w), bf_hi(w.w)}; }
;     __device__ __forceinline__ void operator()(AccT& acc, const Unit& u, int wr, int wc, int fr, int fq) const {
;     ...
;             for (int m = 0; m < 4; ++m) { const size_t row = (size_t)(row0 + ai * 128 + m * 16);
; #pragma unroll
;                 for (int bj = 0; bj < 2; ++bj) { f32x4 p0, p1; unpack8(*(const u32x4*)(PROJ + row * DIN + 8192 + col0 + bj * 128), p0, p1);
; #pragma unroll
;                     for (int j = 0; j < 4; ++j) { p0[j] = fmaxf(p0[j], TINY); p1[j] = fmaxf(p1[j], TINY); }
;                     if (u.kind == 0) { f32x4 s0, s1; unpack8(*(const u32x4*)(PROJ + row * DIN + 4096 + col0 + bj * 128), s0, s1);
; #pragma unroll
;                         for (int j = 0; j < 4; ++j) { acc[ai][bj][m][0][j] *= s0[j] * __builtin_amdgcn_rcpf(p0[j]); acc[ai][bj][m][1][j] *= s1[j] * __builtin_amdgcn_rcpf(p1[j]); } }
;                     else *(u32x4*)(MG + row * DM + col0 + bj * 128) = pack8(acc[ai][bj][m][0] * p0, acc[ai][bj][m][1] * p1); } }
	v_lshlrev_b32_e32 v140, 16, v190
	v_and_b32_e32 v141, 0xffff0000, v190
	v_lshlrev_b32_e32 v142, 16, v191
	v_and_b32_e32 v143, 0xffff0000, v191
	v_lshlrev_b32_e32 v144, 16, v192
	v_and_b32_e32 v145, 0xffff0000, v192
	v_lshlrev_b32_e32 v146, 16, v193
	v_and_b32_e32 v147, 0xffff0000, v193
	v_max_f32_e32 v140, v140, v140
	v_max_f32_e32 v141, v141, v141
	v_max_f32_e32 v142, v142, v142
	v_max_f32_e32 v143, v143, v143
	v_max_f32_e32 v144, v144, v144
	v_max_f32_e32 v145, v145, v145
	v_max_f32_e32 v146, v146, v146
	v_max_f32_e32 v147, v147, v147
	v_max_f32_e32 v140, 0xda24260, v140
	v_max_f32_e32 v141, 0xda24260, v141
	v_max_f32_e32 v142, 0xda24260, v142
	v_max_f32_e32 v143, 0xda24260, v143
	v_max_f32_e32 v144, 0xda24260, v144
	v_max_f32_e32 v145, 0xda24260, v145
	v_max_f32_e32 v146, 0xda24260, v146
	v_max_f32_e32 v147, 0xda24260, v147
	v_rcp_f32_e32 v140, v140
	v_rcp_f32_e32 v141, v141
	v_rcp_f32_e32 v142, v142
	v_rcp_f32_e32 v143, v143
	v_rcp_f32_e32 v144, v144
	v_rcp_f32_e32 v145, v145
	v_rcp_f32_e32 v146, v146
	v_rcp_f32_e32 v147, v147
	v_lshlrev_b32_e32 v154, 16, v166
	v_and_b32_e32 v155, 0xffff0000, v166
	v_lshlrev_b32_e32 v156, 16, v167
	v_and_b32_e32 v157, 0xffff0000, v167
	v_lshlrev_b32_e32 v158, 16, v168
	v_and_b32_e32 v159, 0xffff0000, v168
	v_lshlrev_b32_e32 v160, 16, v169
	v_and_b32_e32 v161, 0xffff0000, v169
	global_load_dwordx4 v[190:193], v[226:227], off offset:256
	v_pk_mul_f32 v[140:141], v[140:141], v[154:155]
	v_pk_mul_f32 v[142:143], v[142:143], v[156:157]
	v_pk_mul_f32 v[144:145], v[144:145], v[158:159]
	v_pk_mul_f32 v[146:147], v[146:147], v[160:161]
	v_pk_mul_f32 v[68:69], v[68:69], v[140:141]
	v_pk_mul_f32 v[70:71], v[70:71], v[142:143]
	v_pk_mul_f32 v[64:65], v[64:65], v[144:145]
	v_pk_mul_f32 v[66:67], v[66:67], v[146:147]
	s_waitcnt vmcnt(5)
	v_lshlrev_b32_e32 v140, 16, v194
	v_and_b32_e32 v141, 0xffff0000, v194
	v_lshlrev_b32_e32 v142, 16, v195
	v_and_b32_e32 v143, 0xffff0000, v195
	v_lshlrev_b32_e32 v144, 16, v196
	v_and_b32_e32 v145, 0xffff0000, v196
	v_lshlrev_b32_e32 v146, 16, v197
	v_and_b32_e32 v147, 0xffff0000, v197
	v_max_f32_e32 v140, v140, v140
	v_max_f32_e32 v141, v141, v141
	v_max_f32_e32 v142, v142, v142
	v_max_f32_e32 v143, v143, v143
	v_max_f32_e32 v144, v144, v144
	v_max_f32_e32 v145, v145, v145
	v_max_f32_e32 v146, v146, v146
	v_max_f32_e32 v147, v147, v147
	v_max_f32_e32 v140, 0xda24260, v140
	v_max_f32_e32 v141, 0xda24260, v141
	v_max_f32_e32 v142, 0xda24260, v142
	v_max_f32_e32 v143, 0xda24260, v143
	v_max_f32_e32 v144, 0xda24260, v144
	v_max_f32_e32 v145, 0xda24260, v145
	v_max_f32_e32 v146, 0xda24260, v146
	v_max_f32_e32 v147, 0xda24260, v147
	v_rcp_f32_e32 v140, v140
	v_rcp_f32_e32 v141, v141
	v_rcp_f32_e32 v142, v142
	v_rcp_f32_e32 v143, v143
	v_rcp_f32_e32 v144, v144
	v_rcp_f32_e32 v145, v145
	v_rcp_f32_e32 v146, v146
	v_rcp_f32_e32 v147, v147
	v_lshlrev_b32_e32 v154, 16, v170
	v_and_b32_e32 v155, 0xffff0000, v170
	v_lshlrev_b32_e32 v156, 16, v171
	v_and_b32_e32 v157, 0xffff0000, v171
	v_lshlrev_b32_e32 v158, 16, v172
	v_and_b32_e32 v159, 0xffff0000, v172
	v_lshlrev_b32_e32 v160, 16, v173
	v_and_b32_e32 v161, 0xffff0000, v173
	s_mov_b64 s[4:5], 0x422000
	v_lshl_add_u64 v[226:227], v[136:137], 0, s[4:5]
	global_load_dwordx4 v[194:197], v[226:227], off
	v_pk_mul_f32 v[140:141], v[140:141], v[154:155]
	v_pk_mul_f32 v[142:143], v[142:143], v[156:157]
	v_pk_mul_f32 v[144:145], v[144:145], v[158:159]
	v_pk_mul_f32 v[146:147], v[146:147], v[160:161]
	v_pk_mul_f32 v[60:61], v[60:61], v[140:141]
	v_pk_mul_f32 v[62:63], v[62:63], v[142:143]
	v_pk_mul_f32 v[56:57], v[56:57], v[144:145]
	v_pk_mul_f32 v[58:59], v[58:59], v[146:147]
	s_waitcnt vmcnt(5)
	v_lshlrev_b32_e32 v140, 16, v198
	v_and_b32_e32 v141, 0xffff0000, v198
	v_lshlrev_b32_e32 v142, 16, v199
	v_and_b32_e32 v143, 0xffff0000, v199
	v_lshlrev_b32_e32 v144, 16, v200
	v_and_b32_e32 v145, 0xffff0000, v200
	v_lshlrev_b32_e32 v146, 16, v201
	v_and_b32_e32 v147, 0xffff0000, v201
	v_max_f32_e32 v140, v140, v140
	v_max_f32_e32 v141, v141, v141
	v_max_f32_e32 v142, v142, v142
	v_max_f32_e32 v143, v143, v143
	v_max_f32_e32 v144, v144, v144
	v_max_f32_e32 v145, v145, v145
	v_max_f32_e32 v146, v146, v146
	v_max_f32_e32 v147, v147, v147
	v_max_f32_e32 v140, 0xda24260, v140
	v_max_f32_e32 v141, 0xda24260, v141
	v_max_f32_e32 v142, 0xda24260, v142
	v_max_f32_e32 v143, 0xda24260, v143
	v_max_f32_e32 v144, 0xda24260, v144
	v_max_f32_e32 v145, 0xda24260, v145
	v_max_f32_e32 v146, 0xda24260, v146
	v_max_f32_e32 v147, 0xda24260, v147
	v_rcp_f32_e32 v140, v140
	v_rcp_f32_e32 v141, v141
	v_rcp_f32_e32 v142, v142
	v_rcp_f32_e32 v143, v143
	v_rcp_f32_e32 v144, v144
	v_rcp_f32_e32 v145, v145
	v_rcp_f32_e32 v146, v146
	v_rcp_f32_e32 v147, v147
	v_lshlrev_b32_e32 v154, 16, v174
	v_and_b32_e32 v155, 0xffff0000, v174
	v_lshlrev_b32_e32 v156, 16, v175
	v_and_b32_e32 v157, 0xffff0000, v175
	v_lshlrev_b32_e32 v158, 16, v176
	v_and_b32_e32 v159, 0xffff0000, v176
	v_lshlrev_b32_e32 v160, 16, v177
	v_and_b32_e32 v161, 0xffff0000, v177
	global_load_dwordx4 v[198:201], v[226:227], off offset:256
	v_pk_mul_f32 v[140:141], v[140:141], v[154:155]
	v_pk_mul_f32 v[142:143], v[142:143], v[156:157]
	v_pk_mul_f32 v[144:145], v[144:145], v[158:159]
	v_pk_mul_f32 v[146:147], v[146:147], v[160:161]
	v_pk_mul_f32 v[28:29], v[28:29], v[140:141]
	v_pk_mul_f32 v[30:31], v[30:31], v[142:143]
	v_pk_mul_f32 v[24:25], v[24:25], v[144:145]
	v_pk_mul_f32 v[26:27], v[26:27], v[146:147]
	s_waitcnt vmcnt(5)
; __device__ __forceinline__ u32x4 pack8(const f32x4 v0, const f32x4 v1) { u32x4 w; w.x = cvt_pk_bf16(v0[0], v0[1]); w.y = cvt_pk_bf16(v0[2], v0[3]); w.z = cvt_pk_bf16(v1[0], v1[1]); w.w = cvt_pk_bf16(v1[2], v1[3]); return w; }
; __device__ __forceinline__ void unpack8(const u32x4 w, f32x4& lo, f32x4& hi) { lo = (f32x4){bf_lo(w.x), bf_hi(w.x), bf_lo(w.y), bf_hi(w.y)}; hi = (f32x4){bf_lo(w.z), bf_hi(w.z), bf_lo(w.w), bf_hi(w.w)}; }
;     __device__ __forceinline__ void operator()(AccT& acc, const Unit& u, int wr, int wc, int fr, int fq) const {
;     ...
;             for (int m = 0; m < 4; ++m) { const size_t row = (size_t)(row0 + ai * 128 + m * 16);
; #pragma unroll
;                 for (int bj = 0; bj < 2; ++bj) { f32x4 p0, p1; unpack8(*(const u32x4*)(PROJ + row * DIN + 8192 + col0 + bj * 128), p0, p1);
; #pragma unroll
;                     for (int j = 0; j < 4; ++j) { p0[j] = fmaxf(p0[j], TINY); p1[j] = fmaxf(p1[j], TINY); }
;                     if (u.kind == 0) { f32x4 s0, s1; unpack8(*(const u32x4*)(PROJ + row * DIN + 4096 + col0 + bj * 128), s0, s1);
; #pragma unroll
;                         for (int j = 0; j < 4; ++j) { acc[ai][bj][m][0][j] *= s0[j] * __builtin_amdgcn_rcpf(p0[j]); acc[ai][bj][m][1][j] *= s1[j] * __builtin_amdgcn_rcpf(p1[j]); } }
;                     else *(u32x4*)(MG + row * DM + col0 + bj * 128) = pack8(acc[ai][bj][m][0] * p0, acc[ai][bj][m][1] * p1); } }
	v_lshlrev_b32_e32 v140, 16, v202
	v_and_b32_e32 v141, 0xffff0000, v202
	v_lshlrev_b32_e32 v142, 16, v203
	v_and_b32_e32 v143, 0xffff0000, v203
	v_lshlrev_b32_e32 v144, 16, v204
	v_and_b32_e32 v145, 0xffff0000, v204
	v_lshlrev_b32_e32 v146, 16, v205
	v_and_b32_e32 v147, 0xffff0000, v205
	v_max_f32_e32 v140, v140, v140
	v_max_f32_e32 v141, v141, v141
	v_max_f32_e32 v142, v142, v142
	v_max_f32_e32 v143, v143, v143
	v_max_f32_e32 v144, v144, v144
	v_max_f32_e32 v145, v145, v145
	v_max_f32_e32 v146, v146, v146
	v_max_f32_e32 v147, v147, v147
	v_max_f32_e32 v140, 0xda24260, v140
	v_max_f32_e32 v141, 0xda24260, v141
	v_max_f32_e32 v142, 0xda24260, v142
	v_max_f32_e32 v143, 0xda24260, v143
	v_max_f32_e32 v144, 0xda24260, v144
	v_max_f32_e32 v145, 0xda24260, v145
	v_max_f32_e32 v146, 0xda24260, v146
	v_max_f32_e32 v147, 0xda24260, v147
	v_rcp_f32_e32 v140, v140
	v_rcp_f32_e32 v141, v141
	v_rcp_f32_e32 v142, v142
	v_rcp_f32_e32 v143, v143
	v_rcp_f32_e32 v144, v144
	v_rcp_f32_e32 v145, v145
	v_rcp_f32_e32 v146, v146
	v_rcp_f32_e32 v147, v147
	v_lshlrev_b32_e32 v154, 16, v178
	v_and_b32_e32 v155, 0xffff0000, v178
	v_lshlrev_b32_e32 v156, 16, v179
	v_and_b32_e32 v157, 0xffff0000, v179
	v_lshlrev_b32_e32 v158, 16, v180
	v_and_b32_e32 v159, 0xffff0000, v180
	v_lshlrev_b32_e32 v160, 16, v181
	v_and_b32_e32 v161, 0xffff0000, v181
	v_pk_mul_f32 v[140:141], v[140:141], v[154:155]
	v_pk_mul_f32 v[142:143], v[142:143], v[156:157]
	v_pk_mul_f32 v[144:145], v[144:145], v[158:159]
	v_pk_mul_f32 v[146:147], v[146:147], v[160:161]
	v_pk_mul_f32 v[52:53], v[52:53], v[140:141]
	v_pk_mul_f32 v[54:55], v[54:55], v[142:143]
	v_pk_mul_f32 v[48:49], v[48:49], v[144:145]
	v_pk_mul_f32 v[50:51], v[50:51], v[146:147]
	s_waitcnt vmcnt(4)
	v_lshlrev_b32_e32 v140, 16, v206
	v_and_b32_e32 v141, 0xffff0000, v206
	v_lshlrev_b32_e32 v142, 16, v207
	v_and_b32_e32 v143, 0xffff0000, v207
	v_lshlrev_b32_e32 v144, 16, v208
	v_and_b32_e32 v145, 0xffff0000, v208
	v_lshlrev_b32_e32 v146, 16, v209
	v_and_b32_e32 v147, 0xffff0000, v209
	v_max_f32_e32 v140, v140, v140
	v_max_f32_e32 v141, v141, v141
	v_max_f32_e32 v142, v142, v142
	v_max_f32_e32 v143, v143, v143
	v_max_f32_e32 v144, v144, v144
	v_max_f32_e32 v145, v145, v145
	v_max_f32_e32 v146, v146, v146
	v_max_f32_e32 v147, v147, v147
	v_max_f32_e32 v140, 0xda24260, v140
	v_max_f32_e32 v141, 0xda24260, v141
	v_max_f32_e32 v142, 0xda24260, v142
	v_max_f32_e32 v143, 0xda24260, v143
	v_max_f32_e32 v144, 0xda24260, v144
	v_max_f32_e32 v145, 0xda24260, v145
	v_max_f32_e32 v146, 0xda24260, v146
	v_max_f32_e32 v147, 0xda24260, v147
	v_rcp_f32_e32 v140, v140
	v_rcp_f32_e32 v141, v141
	v_rcp_f32_e32 v142, v142
	v_rcp_f32_e32 v143, v143
	v_rcp_f32_e32 v144, v144
	v_rcp_f32_e32 v145, v145
	v_rcp_f32_e32 v146, v146
	v_rcp_f32_e32 v147, v147
	v_lshlrev_b32_e32 v154, 16, v182
	v_and_b32_e32 v155, 0xffff0000, v182
	v_lshlrev_b32_e32 v156, 16, v183
	v_and_b32_e32 v157, 0xffff0000, v183
	v_lshlrev_b32_e32 v158, 16, v184
	v_and_b32_e32 v159, 0xffff0000, v184
	v_lshlrev_b32_e32 v160, 16, v185
	v_and_b32_e32 v161, 0xffff0000, v185
	v_pk_mul_f32 v[140:141], v[140:141], v[154:155]
	v_pk_mul_f32 v[142:143], v[142:143], v[156:157]
	v_pk_mul_f32 v[144:145], v[144:145], v[158:159]
	v_pk_mul_f32 v[146:147], v[146:147], v[160:161]
	v_pk_mul_f32 v[20:21], v[20:21], v[140:141]
	v_pk_mul_f32 v[22:23], v[22:23], v[142:143]
	v_pk_mul_f32 v[16:17], v[16:17], v[144:145]
	v_pk_mul_f32 v[18:19], v[18:19], v[146:147]
	s_waitcnt vmcnt(3)
	v_lshlrev_b32_e32 v140, 16, v210
	v_and_b32_e32 v141, 0xffff0000, v210
	v_lshlrev_b32_e32 v142, 16, v211
	v_and_b32_e32 v143, 0xffff0000, v211
	v_lshlrev_b32_e32 v144, 16, v212
	v_and_b32_e32 v145, 0xffff0000, v212
	v_lshlrev_b32_e32 v146, 16, v213
	v_and_b32_e32 v147, 0xffff0000, v213
	v_max_f32_e32 v140, v140, v140
	v_max_f32_e32 v141, v141, v141
	v_max_f32_e32 v142, v142, v142
	v_max_f32_e32 v143, v143, v143
	v_max_f32_e32 v144, v144, v144
	v_max_f32_e32 v145, v145, v145
	v_max_f32_e32 v146, v146, v146
	v_max_f32_e32 v147, v147, v147
	v_max_f32_e32 v140, 0xda24260, v140
	v_max_f32_e32 v141, 0xda24260, v141
	v_max_f32_e32 v142, 0xda24260, v142
	v_max_f32_e32 v143, 0xda24260, v143
	v_max_f32_e32 v144, 0xda24260, v144
	v_max_f32_e32 v145, 0xda24260, v145
	v_max_f32_e32 v146, 0xda24260, v146
	v_max_f32_e32 v147, 0xda24260, v147
	v_rcp_f32_e32 v140, v140
	v_rcp_f32_e32 v141, v141
	v_rcp_f32_e32 v142, v142
	v_rcp_f32_e32 v143, v143
	v_rcp_f32_e32 v144, v144
	v_rcp_f32_e32 v145, v145
	v_rcp_f32_e32 v146, v146
	v_rcp_f32_e32 v147, v147
	v_lshlrev_b32_e32 v154, 16, v186
	v_and_b32_e32 v155, 0xffff0000, v186
	v_lshlrev_b32_e32 v156, 16, v187
	v_and_b32_e32 v157, 0xffff0000, v187
	v_lshlrev_b32_e32 v158, 16, v188
	v_and_b32_e32 v159, 0xffff0000, v188
	v_lshlrev_b32_e32 v160, 16, v189
	v_and_b32_e32 v161, 0xffff0000, v189
	v_pk_mul_f32 v[140:141], v[140:141], v[154:155]
	v_pk_mul_f32 v[142:143], v[142:143], v[156:157]
	v_pk_mul_f32 v[144:145], v[144:145], v[158:159]
	v_pk_mul_f32 v[146:147], v[146:147], v[160:161]
	v_pk_mul_f32 v[44:45], v[44:45], v[140:141]
	v_pk_mul_f32 v[46:47], v[46:47], v[142:143]
	v_pk_mul_f32 v[40:41], v[40:41], v[144:145]
	v_pk_mul_f32 v[42:43], v[42:43], v[146:147]
	s_waitcnt vmcnt(2)
; __device__ __forceinline__ u32x4 pack8(const f32x4 v0, const f32x4 v1) { u32x4 w; w.x = cvt_pk_bf16(v0[0], v0[1]); w.y = cvt_pk_bf16(v0[2], v0[3]); w.z = cvt_pk_bf16(v1[0], v1[1]); w.w = cvt_pk_bf16(v1[2], v1[3]); return w; }
; __device__ __forceinline__ void unpack8(const u32x4 w, f32x4& lo, f32x4& hi) { lo = (f32x4){bf_lo(w.x), bf_hi(w.x), bf_lo(w.y), bf_hi(w.y)}; hi = (f32x4){bf_lo(w.z), bf_hi(w.z), bf_lo(w.w), bf_hi(w.w)}; }
;     __device__ __forceinline__ void operator()(AccT& acc, const Unit& u, int wr, int wc, int fr, int fq) const {
;     ...
;             for (int m = 0; m < 4; ++m) { const size_t row = (size_t)(row0 + ai * 128 + m * 16);
; #pragma unroll
;                 for (int bj = 0; bj < 2; ++bj) { f32x4 p0, p1; unpack8(*(const u32x4*)(PROJ + row * DIN + 8192 + col0 + bj * 128), p0, p1);
; #pragma unroll
;                     for (int j = 0; j < 4; ++j) { p0[j] = fmaxf(p0[j], TINY); p1[j] = fmaxf(p1[j], TINY); }
;                     if (u.kind == 0) { f32x4 s0, s1; unpack8(*(const u32x4*)(PROJ + row * DIN + 4096 + col0 + bj * 128), s0, s1);
; #pragma unroll
;                         for (int j = 0; j < 4; ++j) { acc[ai][bj][m][0][j] *= s0[j] * __builtin_amdgcn_rcpf(p0[j]); acc[ai][bj][m][1][j] *= s1[j] * __builtin_amdgcn_rcpf(p1[j]); } }
;                     else *(u32x4*)(MG + row * DM + col0 + bj * 128) = pack8(acc[ai][bj][m][0] * p0, acc[ai][bj][m][1] * p1); } }
	v_lshlrev_b32_e32 v140, 16, v214
	v_and_b32_e32 v141, 0xffff0000, v214
	v_lshlrev_b32_e32 v142, 16, v215
	v_and_b32_e32 v143, 0xffff0000, v215
	v_lshlrev_b32_e32 v144, 16, v216
	v_and_b32_e32 v145, 0xffff0000, v216
	v_lshlrev_b32_e32 v146, 16, v217
	v_and_b32_e32 v147, 0xffff0000, v217
	v_max_f32_e32 v140, v140, v140
	v_max_f32_e32 v141, v141, v141
	v_max_f32_e32 v142, v142, v142
	v_max_f32_e32 v143, v143, v143
	v_max_f32_e32 v144, v144, v144
	v_max_f32_e32 v145, v145, v145
	v_max_f32_e32 v146, v146, v146
	v_max_f32_e32 v147, v147, v147
	v_max_f32_e32 v140, 0xda24260, v140
	v_max_f32_e32 v141, 0xda24260, v141
	v_max_f32_e32 v142, 0xda24260, v142
	v_max_f32_e32 v143, 0xda24260, v143
	v_max_f32_e32 v144, 0xda24260, v144
	v_max_f32_e32 v145, 0xda24260, v145
	v_max_f32_e32 v146, 0xda24260, v146
	v_max_f32_e32 v147, 0xda24260, v147
	v_rcp_f32_e32 v140, v140
	v_rcp_f32_e32 v141, v141
	v_rcp_f32_e32 v142, v142
	v_rcp_f32_e32 v143, v143
	v_rcp_f32_e32 v144, v144
	v_rcp_f32_e32 v145, v145
	v_rcp_f32_e32 v146, v146
	v_rcp_f32_e32 v147, v147
	v_lshlrev_b32_e32 v154, 16, v190
	v_and_b32_e32 v155, 0xffff0000, v190
	v_lshlrev_b32_e32 v156, 16, v191
	v_and_b32_e32 v157, 0xffff0000, v191
	v_lshlrev_b32_e32 v158, 16, v192
	v_and_b32_e32 v159, 0xffff0000, v192
	v_lshlrev_b32_e32 v160, 16, v193
	v_and_b32_e32 v161, 0xffff0000, v193
	v_pk_mul_f32 v[140:141], v[140:141], v[154:155]
	v_pk_mul_f32 v[142:143], v[142:143], v[156:157]
	v_pk_mul_f32 v[144:145], v[144:145], v[158:159]
	v_pk_mul_f32 v[146:147], v[146:147], v[160:161]
	v_pk_mul_f32 v[12:13], v[12:13], v[140:141]
	v_pk_mul_f32 v[14:15], v[14:15], v[142:143]
	v_pk_mul_f32 v[8:9], v[8:9], v[144:145]
	v_pk_mul_f32 v[10:11], v[10:11], v[146:147]
	s_waitcnt vmcnt(1)
	v_lshlrev_b32_e32 v140, 16, v218
	v_and_b32_e32 v141, 0xffff0000, v218
	v_lshlrev_b32_e32 v142, 16, v219
	v_and_b32_e32 v143, 0xffff0000, v219
	v_lshlrev_b32_e32 v144, 16, v220
	v_and_b32_e32 v145, 0xffff0000, v220
	v_lshlrev_b32_e32 v146, 16, v221
	v_and_b32_e32 v147, 0xffff0000, v221
	v_max_f32_e32 v140, v140, v140
	v_max_f32_e32 v141, v141, v141
	v_max_f32_e32 v142, v142, v142
	v_max_f32_e32 v143, v143, v143
	v_max_f32_e32 v144, v144, v144
	v_max_f32_e32 v145, v145, v145
	v_max_f32_e32 v146, v146, v146
	v_max_f32_e32 v147, v147, v147
	v_max_f32_e32 v140, 0xda24260, v140
	v_max_f32_e32 v141, 0xda24260, v141
	v_max_f32_e32 v142, 0xda24260, v142
	v_max_f32_e32 v143, 0xda24260, v143
	v_max_f32_e32 v144, 0xda24260, v144
	v_max_f32_e32 v145, 0xda24260, v145
	v_max_f32_e32 v146, 0xda24260, v146
	v_max_f32_e32 v147, 0xda24260, v147
	v_rcp_f32_e32 v140, v140
	v_rcp_f32_e32 v141, v141
	v_rcp_f32_e32 v142, v142
	v_rcp_f32_e32 v143, v143
	v_rcp_f32_e32 v144, v144
	v_rcp_f32_e32 v145, v145
	v_rcp_f32_e32 v146, v146
	v_rcp_f32_e32 v147, v147
	v_lshlrev_b32_e32 v154, 16, v194
	v_and_b32_e32 v155, 0xffff0000, v194
	v_lshlrev_b32_e32 v156, 16, v195
	v_and_b32_e32 v157, 0xffff0000, v195
	v_lshlrev_b32_e32 v158, 16, v196
	v_and_b32_e32 v159, 0xffff0000, v196
	v_lshlrev_b32_e32 v160, 16, v197
	v_and_b32_e32 v161, 0xffff0000, v197
	v_pk_mul_f32 v[140:141], v[140:141], v[154:155]
	v_pk_mul_f32 v[142:143], v[142:143], v[156:157]
	v_pk_mul_f32 v[144:145], v[144:145], v[158:159]
	v_pk_mul_f32 v[146:147], v[146:147], v[160:161]
	v_pk_mul_f32 v[36:37], v[36:37], v[140:141]
	v_pk_mul_f32 v[38:39], v[38:39], v[142:143]
	v_pk_mul_f32 v[32:33], v[32:33], v[144:145]
	v_pk_mul_f32 v[34:35], v[34:35], v[146:147]
	s_waitcnt vmcnt(0)
	v_lshlrev_b32_e32 v140, 16, v222
	v_and_b32_e32 v141, 0xffff0000, v222
	v_lshlrev_b32_e32 v142, 16, v223
	v_and_b32_e32 v143, 0xffff0000, v223
	v_lshlrev_b32_e32 v144, 16, v224
	v_and_b32_e32 v145, 0xffff0000, v224
	v_lshlrev_b32_e32 v146, 16, v225
	v_and_b32_e32 v147, 0xffff0000, v225
	v_max_f32_e32 v140, v140, v140
	v_max_f32_e32 v141, v141, v141
	v_max_f32_e32 v142, v142, v142
	v_max_f32_e32 v143, v143, v143
	v_max_f32_e32 v144, v144, v144
	v_max_f32_e32 v145, v145, v145
	v_max_f32_e32 v146, v146, v146
	v_max_f32_e32 v147, v147, v147
	v_max_f32_e32 v140, 0xda24260, v140
	v_max_f32_e32 v141, 0xda24260, v141
	v_max_f32_e32 v142, 0xda24260, v142
	v_max_f32_e32 v143, 0xda24260, v143
	v_max_f32_e32 v144, 0xda24260, v144
	v_max_f32_e32 v145, 0xda24260, v145
	v_max_f32_e32 v146, 0xda24260, v146
	v_max_f32_e32 v147, 0xda24260, v147
	v_rcp_f32_e32 v140, v140
	v_rcp_f32_e32 v141, v141
	v_rcp_f32_e32 v142, v142
	v_rcp_f32_e32 v143, v143
	v_rcp_f32_e32 v144, v144
	v_rcp_f32_e32 v145, v145
	v_rcp_f32_e32 v146, v146
	v_rcp_f32_e32 v147, v147
	v_lshlrev_b32_e32 v154, 16, v198
	v_and_b32_e32 v155, 0xffff0000, v198
	v_lshlrev_b32_e32 v156, 16, v199
	v_and_b32_e32 v157, 0xffff0000, v199
	v_lshlrev_b32_e32 v158, 16, v200
	v_and_b32_e32 v159, 0xffff0000, v200
	v_lshlrev_b32_e32 v160, 16, v201
	v_and_b32_e32 v161, 0xffff0000, v201
	v_pk_mul_f32 v[140:141], v[140:141], v[154:155]
	v_pk_mul_f32 v[142:143], v[142:143], v[156:157]
	v_pk_mul_f32 v[144:145], v[144:145], v[158:159]
	v_pk_mul_f32 v[146:147], v[146:147], v[160:161]
	v_pk_mul_f32 v[4:5], v[4:5], v[140:141]
	v_pk_mul_f32 v[6:7], v[6:7], v[142:143]
	v_pk_mul_f32 v[0:1], v[0:1], v[144:145]
	v_pk_mul_f32 v[2:3], v[2:3], v[146:147]
	s_branch .Lbr_done
; __device__ __forceinline__ u32x4 pack8(const f32x4 v0, const f32x4 v1) { u32x4 w; w.x = cvt_pk_bf16(v0[0], v0[1]); w.y = cvt_pk_bf16(v0[2], v0[3]); w.z = cvt_pk_bf16(v1[0], v1[1]); w.w = cvt_pk_bf16(v1[2], v1[3]); return w; }
; __device__ __forceinline__ void unpack8(const u32x4 w, f32x4& lo, f32x4& hi) { lo = (f32x4){bf_lo(w.x), bf_hi(w.x), bf_lo(w.y), bf_hi(w.y)}; hi = (f32x4){bf_lo(w.z), bf_hi(w.z), bf_lo(w.w), bf_hi(w.w)}; }
;     __device__ __forceinline__ void operator()(AccT& acc, const Unit& u, int wr, int wc, int fr, int fq) const {
;     ...
;             for (int m = 0; m < 4; ++m) { const size_t row = (size_t)(row0 + ai * 128 + m * 16);
; #pragma unroll
;                 for (int bj = 0; bj < 2; ++bj) { f32x4 p0, p1; unpack8(*(const u32x4*)(PROJ + row * DIN + 8192 + col0 + bj * 128), p0, p1);
; #pragma unroll
;                     for (int j = 0; j < 4; ++j) { p0[j] = fmaxf(p0[j], TINY); p1[j] = fmaxf(p1[j], TINY); }
;                     if (u.kind == 0) { f32x4 s0, s1; unpack8(*(const u32x4*)(PROJ + row * DIN + 4096 + col0 + bj * 128), s0, s1);
; #pragma unroll
;                         for (int j = 0; j < 4; ++j) { acc[ai][bj][m][0][j] *= s0[j] * __builtin_amdgcn_rcpf(p0[j]); acc[ai][bj][m][1][j] *= s1[j] * __builtin_amdgcn_rcpf(p1[j]); } }
;                     else *(u32x4*)(MG + row * DM + col0 + bj * 128) = pack8(acc[ai][bj][m][0] * p0, acc[ai][bj][m][1] * p1); } }
.Lbr_kind1:
	s_mov_b64 s[4:5], 0x0
	v_lshl_add_u64 v[226:227], v[138:139], 0, s[4:5]
	s_waitcnt vmcnt(15)
	v_lshlrev_b32_e32 v140, 16, v162
	v_and_b32_e32 v141, 0xffff0000, v162
	v_lshlrev_b32_e32 v142, 16, v163
	v_and_b32_e32 v143, 0xffff0000, v163
	v_lshlrev_b32_e32 v144, 16, v164
	v_and_b32_e32 v145, 0xffff0000, v164
	v_lshlrev_b32_e32 v146, 16, v165
	v_and_b32_e32 v147, 0xffff0000, v165
	v_max_f32_e32 v140, v140, v140
	v_max_f32_e32 v141, v141, v141
	v_max_f32_e32 v142, v142, v142
	v_max_f32_e32 v143, v143, v143
	v_max_f32_e32 v144, v144, v144
	v_max_f32_e32 v145, v145, v145
	v_max_f32_e32 v146, v146, v146
	v_max_f32_e32 v147, v147, v147
	v_max_f32_e32 v140, 0xda24260, v140
	v_max_f32_e32 v141, 0xda24260, v141
	v_max_f32_e32 v142, 0xda24260, v142
	v_max_f32_e32 v143, 0xda24260, v143
	v_max_f32_e32 v144, 0xda24260, v144
	v_max_f32_e32 v145, 0xda24260, v145
	v_max_f32_e32 v146, 0xda24260, v146
	v_max_f32_e32 v147, 0xda24260, v147
	v_pk_mul_f32 v[154:155], v[124:125], v[140:141]
	v_pk_mul_f32 v[156:157], v[126:127], v[142:143]
	v_pk_mul_f32 v[158:159], v[120:121], v[144:145]
	v_pk_mul_f32 v[160:161], v[122:123], v[146:147]
	v_cvt_pk_bf16_f32 v132, v154, v155
	v_cvt_pk_bf16_f32 v133, v156, v157
	v_cvt_pk_bf16_f32 v134, v158, v159
	v_cvt_pk_bf16_f32 v135, v160, v161
	global_store_dwordx4 v[226:227], v[132:135], off
	s_waitcnt vmcnt(15)
	v_lshlrev_b32_e32 v140, 16, v166
	v_and_b32_e32 v141, 0xffff0000, v166
	v_lshlrev_b32_e32 v142, 16, v167
	v_and_b32_e32 v143, 0xffff0000, v167
	v_lshlrev_b32_e32 v144, 16, v168
	v_and_b32_e32 v145, 0xffff0000, v168
	v_lshlrev_b32_e32 v146, 16, v169
	v_and_b32_e32 v147, 0xffff0000, v169
	v_max_f32_e32 v140, v140, v140
	v_max_f32_e32 v141, v141, v141
	v_max_f32_e32 v142, v142, v142
	v_max_f32_e32 v143, v143, v143
	v_max_f32_e32 v144, v144, v144
	v_max_f32_e32 v145, v145, v145
	v_max_f32_e32 v146, v146, v146
	v_max_f32_e32 v147, v147, v147
	v_max_f32_e32 v140, 0xda24260, v140
	v_max_f32_e32 v141, 0xda24260, v141
	v_max_f32_e32 v142, 0xda24260, v142
	v_max_f32_e32 v143, 0xda24260, v143
	v_max_f32_e32 v144, 0xda24260, v144
	v_max_f32_e32 v145, 0xda24260, v145
	v_max_f32_e32 v146, 0xda24260, v146
	v_max_f32_e32 v147, 0xda24260, v147
	v_pk_mul_f32 v[154:155], v[92:93], v[140:141]
	v_pk_mul_f32 v[156:157], v[94:95], v[142:143]
	v_pk_mul_f32 v[158:159], v[88:89], v[144:145]
	v_pk_mul_f32 v[160:161], v[90:91], v[146:147]
	v_cvt_pk_bf16_f32 v132, v154, v155
	v_cvt_pk_bf16_f32 v133, v156, v157
	v_cvt_pk_bf16_f32 v134, v158, v159
	v_cvt_pk_bf16_f32 v135, v160, v161
	global_store_dwordx4 v[226:227], v[132:135], off offset:256
	s_mov_b64 s[4:5], 0x20000
	v_lshl_add_u64 v[226:227], v[138:139], 0, s[4:5]
	s_waitcnt vmcnt(15)
	v_lshlrev_b32_e32 v140, 16, v170
	v_and_b32_e32 v141, 0xffff0000, v170
	v_lshlrev_b32_e32 v142, 16, v171
	v_and_b32_e32 v143, 0xffff0000, v171
	v_lshlrev_b32_e32 v144, 16, v172
	v_and_b32_e32 v145, 0xffff0000, v172
	v_lshlrev_b32_e32 v146, 16, v173
	v_and_b32_e32 v147, 0xffff0000, v173
	v_max_f32_e32 v140, v140, v140
	v_max_f32_e32 v141, v141, v141
	v_max_f32_e32 v142, v142, v142
	v_max_f32_e32 v143, v143, v143
	v_max_f32_e32 v144, v144, v144
	v_max_f32_e32 v145, v145, v145
	v_max_f32_e32 v146, v146, v146
	v_max_f32_e32 v147, v147, v147
	v_max_f32_e32 v140, 0xda24260, v140
	v_max_f32_e32 v141, 0xda24260, v141
	v_max_f32_e32 v142, 0xda24260, v142
	v_max_f32_e32 v143, 0xda24260, v143
	v_max_f32_e32 v144, 0xda24260, v144
	v_max_f32_e32 v145, 0xda24260, v145
	v_max_f32_e32 v146, 0xda24260, v146
	v_max_f32_e32 v147, 0xda24260, v147
	v_pk_mul_f32 v[154:155], v[116:117], v[140:141]
	v_pk_mul_f32 v[156:157], v[118:119], v[142:143]
	v_pk_mul_f32 v[158:159], v[112:113], v[144:145]
	v_pk_mul_f32 v[160:161], v[114:115], v[146:147]
	v_cvt_pk_bf16_f32 v132, v154, v155
	v_cvt_pk_bf16_f32 v133, v156, v157
	v_cvt_pk_bf16_f32 v134, v158, v159
	v_cvt_pk_bf16_f32 v135, v160, v161
	global_store_dwordx4 v[226:227], v[132:135], off
	s_waitcnt vmcnt(15)
	v_lshlrev_b32_e32 v140, 16, v174
	v_and_b32_e32 v141, 0xffff0000, v174
	v_lshlrev_b32_e32 v142, 16, v175
	v_and_b32_e32 v143, 0xffff0000, v175
	v_lshlrev_b32_e32 v144, 16, v176
	v_and_b32_e32 v145, 0xffff0000, v176
	v_lshlrev_b32_e32 v146, 16, v177
	v_and_b32_e32 v147, 0xffff0000, v177
	v_max_f32_e32 v140, v140, v140
	v_max_f32_e32 v141, v141, v141
	v_max_f32_e32 v142, v142, v142
	v_max_f32_e32 v143, v143, v143
	v_max_f32_e32 v144, v144, v144
	v_max_f32_e32 v145, v145, v145
	v_max_f32_e32 v146, v146, v146
	v_max_f32_e32 v147, v147, v147
	v_max_f32_e32 v140, 0xda24260, v140
	v_max_f32_e32 v141, 0xda24260, v141
	v_max_f32_e32 v142, 0xda24260, v142
	v_max_f32_e32 v143, 0xda24260, v143
	v_max_f32_e32 v144, 0xda24260, v144
	v_max_f32_e32 v145, 0xda24260, v145
	v_max_f32_e32 v146, 0xda24260, v146
	v_max_f32_e32 v147, 0xda24260, v147
	v_pk_mul_f32 v[154:155], v[84:85], v[140:141]
	v_pk_mul_f32 v[156:157], v[86:87], v[142:143]
	v_pk_mul_f32 v[158:159], v[80:81], v[144:145]
	v_pk_mul_f32 v[160:161], v[82:83], v[146:147]
	v_cvt_pk_bf16_f32 v132, v154, v155
	v_cvt_pk_bf16_f32 v133, v156, v157
	v_cvt_pk_bf16_f32 v134, v158, v159
	v_cvt_pk_bf16_f32 v135, v160, v161
	global_store_dwordx4 v[226:227], v[132:135], off offset:256
	s_mov_b64 s[4:5], 0x40000
	v_lshl_add_u64 v[226:227], v[138:139], 0, s[4:5]
	s_waitcnt vmcnt(15)
; __device__ __forceinline__ u32x4 pack8(const f32x4 v0, const f32x4 v1) { u32x4 w; w.x = cvt_pk_bf16(v0[0], v0[1]); w.y = cvt_pk_bf16(v0[2], v0[3]); w.z = cvt_pk_bf16(v1[0], v1[1]); w.w = cvt_pk_bf16(v1[2], v1[3]); return w; }
; __device__ __forceinline__ void unpack8(const u32x4 w, f32x4& lo, f32x4& hi) { lo = (f32x4){bf_lo(w.x), bf_hi(w.x), bf_lo(w.y), bf_hi(w.y)}; hi = (f32x4){bf_lo(w.z), bf_hi(w.z), bf_lo(w.w), bf_hi(w.w)}; }
;     __device__ __forceinline__ void operator()(AccT& acc, const Unit& u, int wr, int wc, int fr, int fq) const {
;     ...
;             for (int m = 0; m < 4; ++m) { const size_t row = (size_t)(row0 + ai * 128 + m * 16);
; #pragma unroll
;                 for (int bj = 0; bj < 2; ++bj) { f32x4 p0, p1; unpack8(*(const u32x4*)(PROJ + row * DIN + 8192 + col0 + bj * 128), p0, p1);
; #pragma unroll
;                     for (int j = 0; j < 4; ++j) { p0[j] = fmaxf(p0[j], TINY); p1[j] = fmaxf(p1[j], TINY); }
;                     if (u.kind == 0) { f32x4 s0, s1; unpack8(*(const u32x4*)(PROJ + row * DIN + 4096 + col0 + bj * 128), s0, s1);
; #pragma unroll
;                         for (int j = 0; j < 4; ++j) { acc[ai][bj][m][0][j] *= s0[j] * __builtin_amdgcn_rcpf(p0[j]); acc[ai][bj][m][1][j] *= s1[j] * __builtin_amdgcn_rcpf(p1[j]); } }
;                     else *(u32x4*)(MG + row * DM + col0 + bj * 128) = pack8(acc[ai][bj][m][0] * p0, acc[ai][bj][m][1] * p1); } }
	v_lshlrev_b32_e32 v140, 16, v178
	v_and_b32_e32 v141, 0xffff0000, v178
	v_lshlrev_b32_e32 v142, 16, v179
	v_and_b32_e32 v143, 0xffff0000, v179
	v_lshlrev_b32_e32 v144, 16, v180
	v_and_b32_e32 v145, 0xffff0000, v180
	v_lshlrev_b32_e32 v146, 16, v181
	v_and_b32_e32 v147, 0xffff0000, v181
	v_max_f32_e32 v140, v140, v140
	v_max_f32_e32 v141, v141, v141
	v_max_f32_e32 v142, v142, v142
	v_max_f32_e32 v143, v143, v143
	v_max_f32_e32 v144, v144, v144
	v_max_f32_e32 v145, v145, v145
	v_max_f32_e32 v146, v146, v146
	v_max_f32_e32 v147, v147, v147
	v_max_f32_e32 v140, 0xda24260, v140
	v_max_f32_e32 v141, 0xda24260, v141
	v_max_f32_e32 v142, 0xda24260, v142
	v_max_f32_e32 v143, 0xda24260, v143
	v_max_f32_e32 v144, 0xda24260, v144
	v_max_f32_e32 v145, 0xda24260, v145
	v_max_f32_e32 v146, 0xda24260, v146
	v_max_f32_e32 v147, 0xda24260, v147
	v_pk_mul_f32 v[154:155], v[108:109], v[140:141]
	v_pk_mul_f32 v[156:157], v[110:111], v[142:143]
	v_pk_mul_f32 v[158:159], v[104:105], v[144:145]
	v_pk_mul_f32 v[160:161], v[106:107], v[146:147]
	v_cvt_pk_bf16_f32 v132, v154, v155
	v_cvt_pk_bf16_f32 v133, v156, v157
	v_cvt_pk_bf16_f32 v134, v158, v159
	v_cvt_pk_bf16_f32 v135, v160, v161
	global_store_dwordx4 v[226:227], v[132:135], off
	s_waitcnt vmcnt(15)
	v_lshlrev_b32_e32 v140, 16, v182
	v_and_b32_e32 v141, 0xffff0000, v182
	v_lshlrev_b32_e32 v142, 16, v183
	v_and_b32_e32 v143, 0xffff0000, v183
	v_lshlrev_b32_e32 v144, 16, v184
	v_and_b32_e32 v145, 0xffff0000, v184
	v_lshlrev_b32_e32 v146, 16, v185
	v_and_b32_e32 v147, 0xffff0000, v185
	v_max_f32_e32 v140, v140, v140
	v_max_f32_e32 v141, v141, v141
	v_max_f32_e32 v142, v142, v142
	v_max_f32_e32 v143, v143, v143
	v_max_f32_e32 v144, v144, v144
	v_max_f32_e32 v145, v145, v145
	v_max_f32_e32 v146, v146, v146
	v_max_f32_e32 v147, v147, v147
	v_max_f32_e32 v140, 0xda24260, v140
	v_max_f32_e32 v141, 0xda24260, v141
	v_max_f32_e32 v142, 0xda24260, v142
	v_max_f32_e32 v143, 0xda24260, v143
	v_max_f32_e32 v144, 0xda24260, v144
	v_max_f32_e32 v145, 0xda24260, v145
	v_max_f32_e32 v146, 0xda24260, v146
	v_max_f32_e32 v147, 0xda24260, v147
	v_pk_mul_f32 v[154:155], v[76:77], v[140:141]
	v_pk_mul_f32 v[156:157], v[78:79], v[142:143]
	v_pk_mul_f32 v[158:159], v[72:73], v[144:145]
	v_pk_mul_f32 v[160:161], v[74:75], v[146:147]
	v_cvt_pk_bf16_f32 v132, v154, v155
	v_cvt_pk_bf16_f32 v133, v156, v157
	v_cvt_pk_bf16_f32 v134, v158, v159
	v_cvt_pk_bf16_f32 v135, v160, v161
	global_store_dwordx4 v[226:227], v[132:135], off offset:256
	s_mov_b64 s[4:5], 0x60000
	v_lshl_add_u64 v[226:227], v[138:139], 0, s[4:5]
	s_waitcnt vmcnt(15)
	v_lshlrev_b32_e32 v140, 16, v186
	v_and_b32_e32 v141, 0xffff0000, v186
	v_lshlrev_b32_e32 v142, 16, v187
	v_and_b32_e32 v143, 0xffff0000, v187
	v_lshlrev_b32_e32 v144, 16, v188
	v_and_b32_e32 v145, 0xffff0000, v188
	v_lshlrev_b32_e32 v146, 16, v189
	v_and_b32_e32 v147, 0xffff0000, v189
	v_max_f32_e32 v140, v140, v140
	v_max_f32_e32 v141, v141, v141
	v_max_f32_e32 v142, v142, v142
	v_max_f32_e32 v143, v143, v143
	v_max_f32_e32 v144, v144, v144
	v_max_f32_e32 v145, v145, v145
	v_max_f32_e32 v146, v146, v146
	v_max_f32_e32 v147, v147, v147
	v_max_f32_e32 v140, 0xda24260, v140
	v_max_f32_e32 v141, 0xda24260, v141
	v_max_f32_e32 v142, 0xda24260, v142
	v_max_f32_e32 v143, 0xda24260, v143
	v_max_f32_e32 v144, 0xda24260, v144
	v_max_f32_e32 v145, 0xda24260, v145
	v_max_f32_e32 v146, 0xda24260, v146
	v_max_f32_e32 v147, 0xda24260, v147
	v_pk_mul_f32 v[154:155], v[100:101], v[140:141]
	v_pk_mul_f32 v[156:157], v[102:103], v[142:143]
	v_pk_mul_f32 v[158:159], v[96:97], v[144:145]
	v_pk_mul_f32 v[160:161], v[98:99], v[146:147]
	v_cvt_pk_bf16_f32 v132, v154, v155
	v_cvt_pk_bf16_f32 v133, v156, v157
	v_cvt_pk_bf16_f32 v134, v158, v159
	v_cvt_pk_bf16_f32 v135, v160, v161
	global_store_dwordx4 v[226:227], v[132:135], off
	s_waitcnt vmcnt(15)
	v_lshlrev_b32_e32 v140, 16, v190
	v_and_b32_e32 v141, 0xffff0000, v190
	v_lshlrev_b32_e32 v142, 16, v191
	v_and_b32_e32 v143, 0xffff0000, v191
	v_lshlrev_b32_e32 v144, 16, v192
	v_and_b32_e32 v145, 0xffff0000, v192
	v_lshlrev_b32_e32 v146, 16, v193
	v_and_b32_e32 v147, 0xffff0000, v193
	v_max_f32_e32 v140, v140, v140
	v_max_f32_e32 v141, v141, v141
	v_max_f32_e32 v142, v142, v142
	v_max_f32_e32 v143, v143, v143
	v_max_f32_e32 v144, v144, v144
	v_max_f32_e32 v145, v145, v145
	v_max_f32_e32 v146, v146, v146
	v_max_f32_e32 v147, v147, v147
	v_max_f32_e32 v140, 0xda24260, v140
	v_max_f32_e32 v141, 0xda24260, v141
	v_max_f32_e32 v142, 0xda24260, v142
	v_max_f32_e32 v143, 0xda24260, v143
	v_max_f32_e32 v144, 0xda24260, v144
	v_max_f32_e32 v145, 0xda24260, v145
	v_max_f32_e32 v146, 0xda24260, v146
	v_max_f32_e32 v147, 0xda24260, v147
	v_pk_mul_f32 v[154:155], v[68:69], v[140:141]
	v_pk_mul_f32 v[156:157], v[70:71], v[142:143]
	v_pk_mul_f32 v[158:159], v[64:65], v[144:145]
	v_pk_mul_f32 v[160:161], v[66:67], v[146:147]
	v_cvt_pk_bf16_f32 v132, v154, v155
	v_cvt_pk_bf16_f32 v133, v156, v157
	v_cvt_pk_bf16_f32 v134, v158, v159
	v_cvt_pk_bf16_f32 v135, v160, v161
	global_store_dwordx4 v[226:227], v[132:135], off offset:256
	s_mov_b64 s[4:5], 0x100000
	v_lshl_add_u64 v[226:227], v[138:139], 0, s[4:5]
	s_waitcnt vmcnt(15)
; __device__ __forceinline__ u32x4 pack8(const f32x4 v0, const f32x4 v1) { u32x4 w; w.x = cvt_pk_bf16(v0[0], v0[1]); w.y = cvt_pk_bf16(v0[2], v0[3]); w.z = cvt_pk_bf16(v1[0], v1[1]); w.w = cvt_pk_bf16(v1[2], v1[3]); return w; }
; __device__ __forceinline__ void unpack8(const u32x4 w, f32x4& lo, f32x4& hi) { lo = (f32x4){bf_lo(w.x), bf_hi(w.x), bf_lo(w.y), bf_hi(w.y)}; hi = (f32x4){bf_lo(w.z), bf_hi(w.z), bf_lo(w.w), bf_hi(w.w)}; }
;     __device__ __forceinline__ void operator()(AccT& acc, const Unit& u, int wr, int wc, int fr, int fq) const {
;     ...
;             for (int m = 0; m < 4; ++m) { const size_t row = (size_t)(row0 + ai * 128 + m * 16);
; #pragma unroll
;                 for (int bj = 0; bj < 2; ++bj) { f32x4 p0, p1; unpack8(*(const u32x4*)(PROJ + row * DIN + 8192 + col0 + bj * 128), p0, p1);
; #pragma unroll
;                     for (int j = 0; j < 4; ++j) { p0[j] = fmaxf(p0[j], TINY); p1[j] = fmaxf(p1[j], TINY); }
;                     if (u.kind == 0) { f32x4 s0, s1; unpack8(*(const u32x4*)(PROJ + row * DIN + 4096 + col0 + bj * 128), s0, s1);
; #pragma unroll
;                         for (int j = 0; j < 4; ++j) { acc[ai][bj][m][0][j] *= s0[j] * __builtin_amdgcn_rcpf(p0[j]); acc[ai][bj][m][1][j] *= s1[j] * __builtin_amdgcn_rcpf(p1[j]); } }
;                     else *(u32x4*)(MG + row * DM + col0 + bj * 128) = pack8(acc[ai][bj][m][0] * p0, acc[ai][bj][m][1] * p1); } }
	v_lshlrev_b32_e32 v140, 16, v194
	v_and_b32_e32 v141, 0xffff0000, v194
	v_lshlrev_b32_e32 v142, 16, v195
	v_and_b32_e32 v143, 0xffff0000, v195
	v_lshlrev_b32_e32 v144, 16, v196
	v_and_b32_e32 v145, 0xffff0000, v196
	v_lshlrev_b32_e32 v146, 16, v197
	v_and_b32_e32 v147, 0xffff0000, v197
	v_max_f32_e32 v140, v140, v140
	v_max_f32_e32 v141, v141, v141
	v_max_f32_e32 v142, v142, v142
	v_max_f32_e32 v143, v143, v143
	v_max_f32_e32 v144, v144, v144
	v_max_f32_e32 v145, v145, v145
	v_max_f32_e32 v146, v146, v146
	v_max_f32_e32 v147, v147, v147
	v_max_f32_e32 v140, 0xda24260, v140
	v_max_f32_e32 v141, 0xda24260, v141
	v_max_f32_e32 v142, 0xda24260, v142
	v_max_f32_e32 v143, 0xda24260, v143
	v_max_f32_e32 v144, 0xda24260, v144
	v_max_f32_e32 v145, 0xda24260, v145
	v_max_f32_e32 v146, 0xda24260, v146
	v_max_f32_e32 v147, 0xda24260, v147
	v_pk_mul_f32 v[154:155], v[60:61], v[140:141]
	v_pk_mul_f32 v[156:157], v[62:63], v[142:143]
	v_pk_mul_f32 v[158:159], v[56:57], v[144:145]
	v_pk_mul_f32 v[160:161], v[58:59], v[146:147]
	v_cvt_pk_bf16_f32 v132, v154, v155
	v_cvt_pk_bf16_f32 v133, v156, v157
	v_cvt_pk_bf16_f32 v134, v158, v159
	v_cvt_pk_bf16_f32 v135, v160, v161
	global_store_dwordx4 v[226:227], v[132:135], off
	s_waitcnt vmcnt(15)
	v_lshlrev_b32_e32 v140, 16, v198
	v_and_b32_e32 v141, 0xffff0000, v198
	v_lshlrev_b32_e32 v142, 16, v199
	v_and_b32_e32 v143, 0xffff0000, v199
	v_lshlrev_b32_e32 v144, 16, v200
	v_and_b32_e32 v145, 0xffff0000, v200
	v_lshlrev_b32_e32 v146, 16, v201
	v_and_b32_e32 v147, 0xffff0000, v201
	v_max_f32_e32 v140, v140, v140
	v_max_f32_e32 v141, v141, v141
	v_max_f32_e32 v142, v142, v142
	v_max_f32_e32 v143, v143, v143
	v_max_f32_e32 v144, v144, v144
	v_max_f32_e32 v145, v145, v145
	v_max_f32_e32 v146, v146, v146
	v_max_f32_e32 v147, v147, v147
	v_max_f32_e32 v140, 0xda24260, v140
	v_max_f32_e32 v141, 0xda24260, v141
	v_max_f32_e32 v142, 0xda24260, v142
	v_max_f32_e32 v143, 0xda24260, v143
	v_max_f32_e32 v144, 0xda24260, v144
	v_max_f32_e32 v145, 0xda24260, v145
	v_max_f32_e32 v146, 0xda24260, v146
	v_max_f32_e32 v147, 0xda24260, v147
	v_pk_mul_f32 v[154:155], v[28:29], v[140:141]
	v_pk_mul_f32 v[156:157], v[30:31], v[142:143]
	v_pk_mul_f32 v[158:159], v[24:25], v[144:145]
	v_pk_mul_f32 v[160:161], v[26:27], v[146:147]
	v_cvt_pk_bf16_f32 v132, v154, v155
	v_cvt_pk_bf16_f32 v133, v156, v157
	v_cvt_pk_bf16_f32 v134, v158, v159
	v_cvt_pk_bf16_f32 v135, v160, v161
	global_store_dwordx4 v[226:227], v[132:135], off offset:256
	s_mov_b64 s[4:5], 0x120000
	v_lshl_add_u64 v[226:227], v[138:139], 0, s[4:5]
	s_waitcnt vmcnt(15)
	v_lshlrev_b32_e32 v140, 16, v202
	v_and_b32_e32 v141, 0xffff0000, v202
	v_lshlrev_b32_e32 v142, 16, v203
	v_and_b32_e32 v143, 0xffff0000, v203
	v_lshlrev_b32_e32 v144, 16, v204
	v_and_b32_e32 v145, 0xffff0000, v204
	v_lshlrev_b32_e32 v146, 16, v205
	v_and_b32_e32 v147, 0xffff0000, v205
	v_max_f32_e32 v140, v140, v140
	v_max_f32_e32 v141, v141, v141
	v_max_f32_e32 v142, v142, v142
	v_max_f32_e32 v143, v143, v143
	v_max_f32_e32 v144, v144, v144
	v_max_f32_e32 v145, v145, v145
	v_max_f32_e32 v146, v146, v146
	v_max_f32_e32 v147, v147, v147
	v_max_f32_e32 v140, 0xda24260, v140
	v_max_f32_e32 v141, 0xda24260, v141
	v_max_f32_e32 v142, 0xda24260, v142
	v_max_f32_e32 v143, 0xda24260, v143
	v_max_f32_e32 v144, 0xda24260, v144
	v_max_f32_e32 v145, 0xda24260, v145
	v_max_f32_e32 v146, 0xda24260, v146
	v_max_f32_e32 v147, 0xda24260, v147
	v_pk_mul_f32 v[154:155], v[52:53], v[140:141]
	v_pk_mul_f32 v[156:157], v[54:55], v[142:143]
	v_pk_mul_f32 v[158:159], v[48:49], v[144:145]
	v_pk_mul_f32 v[160:161], v[50:51], v[146:147]
	v_cvt_pk_bf16_f32 v132, v154, v155
	v_cvt_pk_bf16_f32 v133, v156, v157
	v_cvt_pk_bf16_f32 v134, v158, v159
	v_cvt_pk_bf16_f32 v135, v160, v161
	global_store_dwordx4 v[226:227], v[132:135], off
	s_waitcnt vmcnt(15)
	v_lshlrev_b32_e32 v140, 16, v206
	v_and_b32_e32 v141, 0xffff0000, v206
	v_lshlrev_b32_e32 v142, 16, v207
	v_and_b32_e32 v143, 0xffff0000, v207
	v_lshlrev_b32_e32 v144, 16, v208
	v_and_b32_e32 v145, 0xffff0000, v208
	v_lshlrev_b32_e32 v146, 16, v209
	v_and_b32_e32 v147, 0xffff0000, v209
	v_max_f32_e32 v140, v140, v140
	v_max_f32_e32 v141, v141, v141
	v_max_f32_e32 v142, v142, v142
	v_max_f32_e32 v143, v143, v143
	v_max_f32_e32 v144, v144, v144
	v_max_f32_e32 v145, v145, v145
	v_max_f32_e32 v146, v146, v146
	v_max_f32_e32 v147, v147, v147
	v_max_f32_e32 v140, 0xda24260, v140
	v_max_f32_e32 v141, 0xda24260, v141
	v_max_f32_e32 v142, 0xda24260, v142
	v_max_f32_e32 v143, 0xda24260, v143
	v_max_f32_e32 v144, 0xda24260, v144
	v_max_f32_e32 v145, 0xda24260, v145
	v_max_f32_e32 v146, 0xda24260, v146
	v_max_f32_e32 v147, 0xda24260, v147
	v_pk_mul_f32 v[154:155], v[20:21], v[140:141]
	v_pk_mul_f32 v[156:157], v[22:23], v[142:143]
	v_pk_mul_f32 v[158:159], v[16:17], v[144:145]
	v_pk_mul_f32 v[160:161], v[18:19], v[146:147]
	v_cvt_pk_bf16_f32 v132, v154, v155
	v_cvt_pk_bf16_f32 v133, v156, v157
	v_cvt_pk_bf16_f32 v134, v158, v159
	v_cvt_pk_bf16_f32 v135, v160, v161
	global_store_dwordx4 v[226:227], v[132:135], off offset:256
	s_mov_b64 s[4:5], 0x140000
	v_lshl_add_u64 v[226:227], v[138:139], 0, s[4:5]
	s_waitcnt vmcnt(15)
; __device__ __forceinline__ u32x4 pack8(const f32x4 v0, const f32x4 v1) { u32x4 w; w.x = cvt_pk_bf16(v0[0], v0[1]); w.y = cvt_pk_bf16(v0[2], v0[3]); w.z = cvt_pk_bf16(v1[0], v1[1]); w.w = cvt_pk_bf16(v1[2], v1[3]); return w; }
; __device__ __forceinline__ void unpack8(const u32x4 w, f32x4& lo, f32x4& hi) { lo = (f32x4){bf_lo(w.x), bf_hi(w.x), bf_lo(w.y), bf_hi(w.y)}; hi = (f32x4){bf_lo(w.z), bf_hi(w.z), bf_lo(w.w), bf_hi(w.w)}; }
;     __device__ __forceinline__ void operator()(AccT& acc, const Unit& u, int wr, int wc, int fr, int fq) const {
;     ...
;             for (int m = 0; m < 4; ++m) { const size_t row = (size_t)(row0 + ai * 128 + m * 16);
; #pragma unroll
;                 for (int bj = 0; bj < 2; ++bj) { f32x4 p0, p1; unpack8(*(const u32x4*)(PROJ + row * DIN + 8192 + col0 + bj * 128), p0, p1);
; #pragma unroll
;                     for (int j = 0; j < 4; ++j) { p0[j] = fmaxf(p0[j], TINY); p1[j] = fmaxf(p1[j], TINY); }
;                     if (u.kind == 0) { f32x4 s0, s1; unpack8(*(const u32x4*)(PROJ + row * DIN + 4096 + col0 + bj * 128), s0, s1);
; #pragma unroll
;                         for (int j = 0; j < 4; ++j) { acc[ai][bj][m][0][j] *= s0[j] * __builtin_amdgcn_rcpf(p0[j]); acc[ai][bj][m][1][j] *= s1[j] * __builtin_amdgcn_rcpf(p1[j]); } }
;                     else *(u32x4*)(MG + row * DM + col0 + bj * 128) = pack8(acc[ai][bj][m][0] * p0, acc[ai][bj][m][1] * p1); } }
	v_lshlrev_b32_e32 v140, 16, v210
	v_and_b32_e32 v141, 0xffff0000, v210
	v_lshlrev_b32_e32 v142, 16, v211
	v_and_b32_e32 v143, 0xffff0000, v211
	v_lshlrev_b32_e32 v144, 16, v212
	v_and_b32_e32 v145, 0xffff0000, v212
	v_lshlrev_b32_e32 v146, 16, v213
	v_and_b32_e32 v147, 0xffff0000, v213
	v_max_f32_e32 v140, v140, v140
	v_max_f32_e32 v141, v141, v141
	v_max_f32_e32 v142, v142, v142
	v_max_f32_e32 v143, v143, v143
	v_max_f32_e32 v144, v144, v144
	v_max_f32_e32 v145, v145, v145
	v_max_f32_e32 v146, v146, v146
	v_max_f32_e32 v147, v147, v147
	v_max_f32_e32 v140, 0xda24260, v140
	v_max_f32_e32 v141, 0xda24260, v141
	v_max_f32_e32 v142, 0xda24260, v142
	v_max_f32_e32 v143, 0xda24260, v143
	v_max_f32_e32 v144, 0xda24260, v144
	v_max_f32_e32 v145, 0xda24260, v145
	v_max_f32_e32 v146, 0xda24260, v146
	v_max_f32_e32 v147, 0xda24260, v147
	v_pk_mul_f32 v[154:155], v[44:45], v[140:141]
	v_pk_mul_f32 v[156:157], v[46:47], v[142:143]
	v_pk_mul_f32 v[158:159], v[40:41], v[144:145]
	v_pk_mul_f32 v[160:161], v[42:43], v[146:147]
	v_cvt_pk_bf16_f32 v132, v154, v155
	v_cvt_pk_bf16_f32 v133, v156, v157
	v_cvt_pk_bf16_f32 v134, v158, v159
	v_cvt_pk_bf16_f32 v135, v160, v161
	global_store_dwordx4 v[226:227], v[132:135], off
	s_waitcnt vmcnt(15)
	v_lshlrev_b32_e32 v140, 16, v214
	v_and_b32_e32 v141, 0xffff0000, v214
	v_lshlrev_b32_e32 v142, 16, v215
	v_and_b32_e32 v143, 0xffff0000, v215
	v_lshlrev_b32_e32 v144, 16, v216
	v_and_b32_e32 v145, 0xffff0000, v216
	v_lshlrev_b32_e32 v146, 16, v217
	v_and_b32_e32 v147, 0xffff0000, v217
	v_max_f32_e32 v140, v140, v140
	v_max_f32_e32 v141, v141, v141
	v_max_f32_e32 v142, v142, v142
	v_max_f32_e32 v143, v143, v143
	v_max_f32_e32 v144, v144, v144
	v_max_f32_e32 v145, v145, v145
	v_max_f32_e32 v146, v146, v146
	v_max_f32_e32 v147, v147, v147
	v_max_f32_e32 v140, 0xda24260, v140
	v_max_f32_e32 v141, 0xda24260, v141
	v_max_f32_e32 v142, 0xda24260, v142
	v_max_f32_e32 v143, 0xda24260, v143
	v_max_f32_e32 v144, 0xda24260, v144
	v_max_f32_e32 v145, 0xda24260, v145
	v_max_f32_e32 v146, 0xda24260, v146
	v_max_f32_e32 v147, 0xda24260, v147
	v_pk_mul_f32 v[154:155], v[12:13], v[140:141]
	v_pk_mul_f32 v[156:157], v[14:15], v[142:143]
	v_pk_mul_f32 v[158:159], v[8:9], v[144:145]
	v_pk_mul_f32 v[160:161], v[10:11], v[146:147]
	v_cvt_pk_bf16_f32 v132, v154, v155
	v_cvt_pk_bf16_f32 v133, v156, v157
	v_cvt_pk_bf16_f32 v134, v158, v159
	v_cvt_pk_bf16_f32 v135, v160, v161
	global_store_dwordx4 v[226:227], v[132:135], off offset:256
	s_mov_b64 s[4:5], 0x160000
	v_lshl_add_u64 v[226:227], v[138:139], 0, s[4:5]
	s_waitcnt vmcnt(15)
	v_lshlrev_b32_e32 v140, 16, v218
	v_and_b32_e32 v141, 0xffff0000, v218
	v_lshlrev_b32_e32 v142, 16, v219
	v_and_b32_e32 v143, 0xffff0000, v219
	v_lshlrev_b32_e32 v144, 16, v220
	v_and_b32_e32 v145, 0xffff0000, v220
	v_lshlrev_b32_e32 v146, 16, v221
	v_and_b32_e32 v147, 0xffff0000, v221
	v_max_f32_e32 v140, v140, v140
	v_max_f32_e32 v141, v141, v141
	v_max_f32_e32 v142, v142, v142
	v_max_f32_e32 v143, v143, v143
	v_max_f32_e32 v144, v144, v144
	v_max_f32_e32 v145, v145, v145
	v_max_f32_e32 v146, v146, v146
	v_max_f32_e32 v147, v147, v147
	v_max_f32_e32 v140, 0xda24260, v140
	v_max_f32_e32 v141, 0xda24260, v141
	v_max_f32_e32 v142, 0xda24260, v142
	v_max_f32_e32 v143, 0xda24260, v143
	v_max_f32_e32 v144, 0xda24260, v144
	v_max_f32_e32 v145, 0xda24260, v145
	v_max_f32_e32 v146, 0xda24260, v146
	v_max_f32_e32 v147, 0xda24260, v147
	v_pk_mul_f32 v[154:155], v[36:37], v[140:141]
	v_pk_mul_f32 v[156:157], v[38:39], v[142:143]
	v_pk_mul_f32 v[158:159], v[32:33], v[144:145]
	v_pk_mul_f32 v[160:161], v[34:35], v[146:147]
	v_cvt_pk_bf16_f32 v132, v154, v155
	v_cvt_pk_bf16_f32 v133, v156, v157
	v_cvt_pk_bf16_f32 v134, v158, v159
	v_cvt_pk_bf16_f32 v135, v160, v161
	global_store_dwordx4 v[226:227], v[132:135], off
	s_waitcnt vmcnt(15)
	v_lshlrev_b32_e32 v140, 16, v222
	v_and_b32_e32 v141, 0xffff0000, v222
	v_lshlrev_b32_e32 v142, 16, v223
	v_and_b32_e32 v143, 0xffff0000, v223
	v_lshlrev_b32_e32 v144, 16, v224
	v_and_b32_e32 v145, 0xffff0000, v224
	v_lshlrev_b32_e32 v146, 16, v225
	v_and_b32_e32 v147, 0xffff0000, v225
	v_max_f32_e32 v140, v140, v140
	v_max_f32_e32 v141, v141, v141
	v_max_f32_e32 v142, v142, v142
	v_max_f32_e32 v143, v143, v143
	v_max_f32_e32 v144, v144, v144
	v_max_f32_e32 v145, v145, v145
	v_max_f32_e32 v146, v146, v146
	v_max_f32_e32 v147, v147, v147
	v_max_f32_e32 v140, 0xda24260, v140
	v_max_f32_e32 v141, 0xda24260, v141
	v_max_f32_e32 v142, 0xda24260, v142
	v_max_f32_e32 v143, 0xda24260, v143
	v_max_f32_e32 v144, 0xda24260, v144
	v_max_f32_e32 v145, 0xda24260, v145
	v_max_f32_e32 v146, 0xda24260, v146
	v_max_f32_e32 v147, 0xda24260, v147
	v_pk_mul_f32 v[154:155], v[4:5], v[140:141]
	v_pk_mul_f32 v[156:157], v[6:7], v[142:143]
	v_pk_mul_f32 v[158:159], v[0:1], v[144:145]
	v_pk_mul_f32 v[160:161], v[2:3], v[146:147]
	v_cvt_pk_bf16_f32 v132, v154, v155
	v_cvt_pk_bf16_f32 v133, v156, v157
	v_cvt_pk_bf16_f32 v134, v158, v159
	v_cvt_pk_bf16_f32 v135, v160, v161
	global_store_dwordx4 v[226:227], v[132:135], off offset:256
.Lbr_done:
	s_not_b64 s[4:5], s[16:17]

; #define PG8_WAIT_V(n) asm volatile("s_waitcnt vmcnt(" #n ")" ::: "memory")
; #define PG8_BAR __builtin_amdgcn_s_barrier()
; template <class Epi, class Sched, bool F8 = false>
; __device__ __forceinline__ void gemm_phase(LAS unsigned char* lds, const int lda, const int ldb, const Sched& S, const Epi& E) {
;     ...
;         cur = nxt; cA = nA; cB = nB; ++ui;
;         if (wr == 1) PG8_BAR;
;     }
;     PG8_WAIT_V(0);
;     PG8_BAR;
.LBB0_539:
	s_andn2_b64 vcc, exec, s[14:15]
	s_cbranch_vccnz .LBB0_480
	s_barrier
	s_branch .LBB0_480
.LBB0_557:
	s_waitcnt vmcnt(0)
	v_readlane_b32 s96, v255, 4
	v_readlane_b32 s88, v255, 7
	v_readlane_b32 s97, v255, 5
	v_readlane_b32 s95, v255, 6
	v_readlane_b32 s89, v255, 8
	s_barrier
